# hand-written ffnconv (layer 0 only): wave-per-channel-strip sweeps, dynamic item queue
# baseline (speedup 1.0000x reference)
.LBB0_1249:
.LBB0_1250:
	s_waitcnt vmcnt(0) lgkmcnt(0)
	s_load_dwordx4 s[0:3], s[92:93], 0xd8
	s_add_u32 s38, s90, 0x15918000
	s_addc_u32 s39, s91, 0
	s_add_u32 s40, s90, 0x21918000
	s_addc_u32 s41, s91, 0
	s_add_u32 s4, s90, 0x2c918080
	s_addc_u32 s5, s91, 0
	v_mov_b32_e32 v4, 0xbfb8aa3b
	v_mov_b32_e32 v5, 0xbfb8aa3b
	v_mov_b32_e32 v6, 1.0
	v_mov_b32_e32 v7, 1.0
	v_mov_b32_e32 v9, 0
	v_mov_b32_e32 v208, 1
	s_waitcnt lgkmcnt(0)
	s_mov_b64 s[44:45], exec
	s_mov_b64 exec, 1
	global_atomic_add v8, v9, v208, s[4:5] sc0
	s_mov_b64 exec, s[44:45]
	s_waitcnt vmcnt(0)
	v_readfirstlane_b32 s6, v8
.Lffn_p9_item:
	s_cmp_ge_u32 s6, 2816
	s_cbranch_scc1 .Lffn_p9_done
	s_mov_b64 s[44:45], exec
	s_mov_b64 exec, 1
	global_atomic_add v8, v9, v208, s[4:5] sc0
	s_mov_b64 exec, s[44:45]
	s_cmp_ge_u32 s6, 1408
	s_cbranch_scc1 .Lffn_p9_ctx
	s_mul_i32 s33, s6, 47663
	s_lshr_b32 s33, s33, 21
	s_mul_i32 s34, s33, 44
	s_sub_u32 s43, s6, s34
	s_and_b32 s34, s33, 1
	s_bfe_u32 s35, s33, 0x20001
	s_lshr_b32 s36, s33, 3
	s_cmp_lg_u32 s35, 0
	s_cselect_b32 s28, -1, 0
	s_cmp_lg_u32 s35, 3
	s_cselect_b32 s29, -1, 0
	s_cmp_lg_u32 s34, 0
	s_cselect_b32 s30, -1, 0
	s_cselect_b32 s31, 0, -1
	s_lshl_b32 s36, s36, 10
	s_lshl_b32 s35, s35, 8
	s_lshl_b32 s34, s34, 5
	s_add_u32 s36, s36, s35
	s_add_u32 s36, s36, s34
	s_add_u32 s36, s36, 4096
	v_and_b32_e32 v1, 63, v154
	v_lshlrev_b32_e32 v1, 2, v1
	s_lshl_b32 s33, s43, 8
	v_add_u32_e32 v1, s33, v1
	v_add_u32_e32 v2, 0x2c00, v1
	v_lshlrev_b32_e32 v3, 1, v1
	s_add_i32 s33, s36, 0
	s_mul_i32 s33, s33, 0x2c00
	s_add_u32 s20, s40, s33
	s_addc_u32 s21, s41, 0
	s_add_i32 s33, s36, 64
	s_mul_i32 s33, s33, 0x2c00
	s_add_u32 s22, s40, s33
	s_addc_u32 s23, s41, 0
	s_add_i32 s33, s36, 128
	s_mul_i32 s33, s33, 0x2c00
	s_add_u32 s24, s40, s33
	s_addc_u32 s25, s41, 0
	s_add_i32 s33, s36, 192
	s_mul_i32 s33, s33, 0x2c00
	s_add_u32 s26, s40, s33
	s_addc_u32 s27, s41, 0
	s_add_i32 s33, s36, -65
	s_mul_i32 s33, s33, 0x5800
	s_ashr_i32 s34, s33, 31
	s_add_u32 s8, s38, s33
	s_addc_u32 s9, s39, s34
	s_add_i32 s33, s36, -1
	s_mul_i32 s33, s33, 0x5800
	s_ashr_i32 s34, s33, 31
	s_add_u32 s10, s38, s33
	s_addc_u32 s11, s39, s34
	s_add_i32 s33, s36, 63
	s_mul_i32 s33, s33, 0x5800
	s_ashr_i32 s34, s33, 31
	s_add_u32 s12, s38, s33
	s_addc_u32 s13, s39, s34
	s_add_i32 s33, s36, 127
	s_mul_i32 s33, s33, 0x5800
	s_ashr_i32 s34, s33, 31
	s_add_u32 s14, s38, s33
	s_addc_u32 s15, s39, s34
	s_add_i32 s33, s36, 191
	s_mul_i32 s33, s33, 0x5800
	s_ashr_i32 s34, s33, 31
	s_add_u32 s16, s38, s33
	s_addc_u32 s17, s39, s34
	s_add_i32 s33, s36, 255
	s_mul_i32 s33, s33, 0x5800
	s_ashr_i32 s34, s33, 31
	s_add_u32 s18, s38, s33
	s_addc_u32 s19, s39, s34
	s_add_u32 s33, s0, 0x0
	s_addc_u32 s34, s1, 0
	s_mov_b32 s36, s33
	s_mov_b32 s37, s34
	global_load_dwordx2 v[10:11], v3, s[36:37]
	s_add_u32 s36, s36, 0x5800
	s_addc_u32 s37, s37, 0
	global_load_dwordx2 v[28:29], v3, s[36:37]
	s_add_u32 s33, s0, 0xb000
	s_addc_u32 s34, s1, 0
	s_mov_b32 s36, s33
	s_mov_b32 s37, s34
	global_load_dwordx2 v[12:13], v3, s[36:37]
	s_add_u32 s36, s36, 0x5800
	s_addc_u32 s37, s37, 0
	global_load_dwordx2 v[30:31], v3, s[36:37]
	s_add_u32 s33, s0, 0x16000
	s_addc_u32 s34, s1, 0
	s_mov_b32 s36, s33
	s_mov_b32 s37, s34
	global_load_dwordx2 v[14:15], v3, s[36:37]
	s_add_u32 s36, s36, 0x5800
	s_addc_u32 s37, s37, 0
	global_load_dwordx2 v[32:33], v3, s[36:37]
	s_add_u32 s33, s0, 0x21000
	s_addc_u32 s34, s1, 0
	s_mov_b32 s36, s33
	s_mov_b32 s37, s34
	global_load_dwordx2 v[16:17], v3, s[36:37]
	s_add_u32 s36, s36, 0x5800
	s_addc_u32 s37, s37, 0
	global_load_dwordx2 v[34:35], v3, s[36:37]
	s_add_u32 s33, s0, 0x2c000
	s_addc_u32 s34, s1, 0
	s_mov_b32 s36, s33
	s_mov_b32 s37, s34
	global_load_dwordx2 v[18:19], v3, s[36:37]
	s_add_u32 s36, s36, 0x5800
	s_addc_u32 s37, s37, 0
	global_load_dwordx2 v[36:37], v3, s[36:37]
	s_add_u32 s33, s0, 0x37000
	s_addc_u32 s34, s1, 0
	s_mov_b32 s36, s33
	s_mov_b32 s37, s34
	global_load_dwordx2 v[20:21], v3, s[36:37]
	s_add_u32 s36, s36, 0x5800
	s_addc_u32 s37, s37, 0
	global_load_dwordx2 v[38:39], v3, s[36:37]
	s_add_u32 s33, s0, 0x42000
	s_addc_u32 s34, s1, 0
	s_mov_b32 s36, s33
	s_mov_b32 s37, s34
	global_load_dwordx2 v[22:23], v3, s[36:37]
	s_add_u32 s36, s36, 0x5800
	s_addc_u32 s37, s37, 0
	global_load_dwordx2 v[40:41], v3, s[36:37]
	s_add_u32 s33, s0, 0x4d000
	s_addc_u32 s34, s1, 0
	s_mov_b32 s36, s33
	s_mov_b32 s37, s34
	global_load_dwordx2 v[24:25], v3, s[36:37]
	s_add_u32 s36, s36, 0x5800
	s_addc_u32 s37, s37, 0
	global_load_dwordx2 v[42:43], v3, s[36:37]
	s_add_u32 s33, s0, 0x58000
	s_addc_u32 s34, s1, 0
	s_mov_b32 s36, s33
	s_mov_b32 s37, s34
	global_load_dwordx2 v[26:27], v3, s[36:37]
	s_add_u32 s36, s36, 0x5800
	s_addc_u32 s37, s37, 0
	global_load_dwordx2 v[44:45], v3, s[36:37]
	global_load_dwordx2 v[46:47], v3, s[2:3]
	s_add_u32 s36, s2, 0x5800
	s_addc_u32 s37, s3, 0
	global_load_dwordx2 v[48:49], v3, s[36:37]
	global_load_dword v180, v1, s[8:9]
	global_load_dword v181, v2, s[8:9]
	global_load_dword v182, v1, s[10:11]
	global_load_dword v183, v2, s[10:11]
	global_load_dword v184, v1, s[12:13]
	global_load_dword v185, v2, s[12:13]
	global_load_dword v186, v1, s[14:15]
	global_load_dword v187, v2, s[14:15]
	global_load_dword v188, v1, s[16:17]
	global_load_dword v189, v2, s[16:17]
	global_load_dword v190, v1, s[18:19]
	global_load_dword v191, v2, s[18:19]
	s_add_u32 s8, s8, 0x5800
	s_addc_u32 s9, s9, 0
	s_add_u32 s10, s10, 0x5800
	s_addc_u32 s11, s11, 0
	s_add_u32 s12, s12, 0x5800
	s_addc_u32 s13, s13, 0
	s_add_u32 s14, s14, 0x5800
	s_addc_u32 s15, s15, 0
	s_add_u32 s16, s16, 0x5800
	s_addc_u32 s17, s17, 0
	s_add_u32 s18, s18, 0x5800
	s_addc_u32 s19, s19, 0
	global_load_dword v192, v1, s[8:9]
	global_load_dword v193, v2, s[8:9]
	global_load_dword v194, v1, s[10:11]
	global_load_dword v195, v2, s[10:11]
	global_load_dword v196, v1, s[12:13]
	global_load_dword v197, v2, s[12:13]
	global_load_dword v198, v1, s[14:15]
	global_load_dword v199, v2, s[14:15]
	global_load_dword v200, v1, s[16:17]
	global_load_dword v201, v2, s[16:17]
	global_load_dword v202, v1, s[18:19]
	global_load_dword v203, v2, s[18:19]
	s_add_u32 s8, s8, 0x5800
	s_addc_u32 s9, s9, 0
	s_add_u32 s10, s10, 0x5800
	s_addc_u32 s11, s11, 0
	s_add_u32 s12, s12, 0x5800
	s_addc_u32 s13, s13, 0
	s_add_u32 s14, s14, 0x5800
	s_addc_u32 s15, s15, 0
	s_add_u32 s16, s16, 0x5800
	s_addc_u32 s17, s17, 0
	s_add_u32 s18, s18, 0x5800
	s_addc_u32 s19, s19, 0
	global_load_dword v156, v1, s[8:9]
	global_load_dword v157, v2, s[8:9]
	global_load_dword v158, v1, s[10:11]
	global_load_dword v159, v2, s[10:11]
	global_load_dword v160, v1, s[12:13]
	global_load_dword v161, v2, s[12:13]
	global_load_dword v162, v1, s[14:15]
	global_load_dword v163, v2, s[14:15]
	global_load_dword v164, v1, s[16:17]
	global_load_dword v165, v2, s[16:17]
	global_load_dword v166, v1, s[18:19]
	global_load_dword v167, v2, s[18:19]
	s_add_u32 s8, s8, 0x5800
	s_addc_u32 s9, s9, 0
	s_add_u32 s10, s10, 0x5800
	s_addc_u32 s11, s11, 0
	s_add_u32 s12, s12, 0x5800
	s_addc_u32 s13, s13, 0
	s_add_u32 s14, s14, 0x5800
	s_addc_u32 s15, s15, 0
	s_add_u32 s16, s16, 0x5800
	s_addc_u32 s17, s17, 0
	s_add_u32 s18, s18, 0x5800
	s_addc_u32 s19, s19, 0
	global_load_dword v168, v1, s[8:9]
	global_load_dword v169, v2, s[8:9]
	global_load_dword v170, v1, s[10:11]
	global_load_dword v171, v2, s[10:11]
	global_load_dword v172, v1, s[12:13]
	global_load_dword v173, v2, s[12:13]
	global_load_dword v174, v1, s[14:15]
	global_load_dword v175, v2, s[14:15]
	global_load_dword v176, v1, s[16:17]
	global_load_dword v177, v2, s[16:17]
	global_load_dword v178, v1, s[18:19]
	global_load_dword v179, v2, s[18:19]
	s_add_u32 s8, s8, 0x5800
	s_addc_u32 s9, s9, 0
	s_add_u32 s10, s10, 0x5800
	s_addc_u32 s11, s11, 0
	s_add_u32 s12, s12, 0x5800
	s_addc_u32 s13, s13, 0
	s_add_u32 s14, s14, 0x5800
	s_addc_u32 s15, s15, 0
	s_add_u32 s16, s16, 0x5800
	s_addc_u32 s17, s17, 0
	s_add_u32 s18, s18, 0x5800
	s_addc_u32 s19, s19, 0
	s_waitcnt vmcnt(24)
	v_and_b32_e32 v180, s30, v180
	v_and_b32_e32 v181, s30, v181
	v_and_b32_e32 v180, s28, v180
	v_and_b32_e32 v181, s28, v181
	v_lshlrev_b32_e32 v50, 16, v180
	v_and_b32_e32 v51, 0xffff0000, v180
	v_lshlrev_b32_e32 v52, 16, v181
	v_and_b32_e32 v53, 0xffff0000, v181
	v_and_b32_e32 v182, s30, v182
	v_and_b32_e32 v183, s30, v183
	v_lshlrev_b32_e32 v54, 16, v182
	v_and_b32_e32 v55, 0xffff0000, v182
	v_lshlrev_b32_e32 v56, 16, v183
	v_and_b32_e32 v57, 0xffff0000, v183
	v_and_b32_e32 v184, s30, v184
	v_and_b32_e32 v185, s30, v185
	v_lshlrev_b32_e32 v58, 16, v184
	v_and_b32_e32 v59, 0xffff0000, v184
	v_lshlrev_b32_e32 v60, 16, v185
	v_and_b32_e32 v61, 0xffff0000, v185
	v_and_b32_e32 v186, s30, v186
	v_and_b32_e32 v187, s30, v187
	v_lshlrev_b32_e32 v62, 16, v186
	v_and_b32_e32 v63, 0xffff0000, v186
	v_lshlrev_b32_e32 v64, 16, v187
	v_and_b32_e32 v65, 0xffff0000, v187
	v_and_b32_e32 v188, s30, v188
	v_and_b32_e32 v189, s30, v189
	v_lshlrev_b32_e32 v66, 16, v188
	v_and_b32_e32 v67, 0xffff0000, v188
	v_lshlrev_b32_e32 v68, 16, v189
	v_and_b32_e32 v69, 0xffff0000, v189
	v_and_b32_e32 v190, s30, v190
	v_and_b32_e32 v191, s30, v191
	v_and_b32_e32 v190, s29, v190
	v_and_b32_e32 v191, s29, v191
	v_lshlrev_b32_e32 v70, 16, v190
	v_and_b32_e32 v71, 0xffff0000, v190
	v_lshlrev_b32_e32 v72, 16, v191
	v_and_b32_e32 v73, 0xffff0000, v191
	v_and_b32_e32 v192, s28, v192
	v_and_b32_e32 v193, s28, v193
	v_lshlrev_b32_e32 v74, 16, v192
	v_and_b32_e32 v75, 0xffff0000, v192
	v_lshlrev_b32_e32 v76, 16, v193
	v_and_b32_e32 v77, 0xffff0000, v193
	v_lshlrev_b32_e32 v78, 16, v194
	v_and_b32_e32 v79, 0xffff0000, v194
	v_lshlrev_b32_e32 v80, 16, v195
	v_and_b32_e32 v81, 0xffff0000, v195
	v_lshlrev_b32_e32 v82, 16, v196
	v_and_b32_e32 v83, 0xffff0000, v196
	v_lshlrev_b32_e32 v84, 16, v197
	v_and_b32_e32 v85, 0xffff0000, v197
	v_lshlrev_b32_e32 v86, 16, v198
	v_and_b32_e32 v87, 0xffff0000, v198
	v_lshlrev_b32_e32 v88, 16, v199
	v_and_b32_e32 v89, 0xffff0000, v199
	v_lshlrev_b32_e32 v90, 16, v200
	v_and_b32_e32 v91, 0xffff0000, v200
	v_lshlrev_b32_e32 v92, 16, v201
	v_and_b32_e32 v93, 0xffff0000, v201
	v_and_b32_e32 v202, s29, v202
	v_and_b32_e32 v203, s29, v203
	v_lshlrev_b32_e32 v94, 16, v202
	v_and_b32_e32 v95, 0xffff0000, v202
	v_lshlrev_b32_e32 v96, 16, v203
	v_and_b32_e32 v97, 0xffff0000, v203
	global_load_dword v180, v1, s[8:9]
	global_load_dword v181, v2, s[8:9]
	global_load_dword v182, v1, s[10:11]
	global_load_dword v183, v2, s[10:11]
	global_load_dword v184, v1, s[12:13]
	global_load_dword v185, v2, s[12:13]
	global_load_dword v186, v1, s[14:15]
	global_load_dword v187, v2, s[14:15]
	global_load_dword v188, v1, s[16:17]
	global_load_dword v189, v2, s[16:17]
	global_load_dword v190, v1, s[18:19]
	global_load_dword v191, v2, s[18:19]
	s_add_u32 s8, s8, 0x5800
	s_addc_u32 s9, s9, 0
	s_add_u32 s10, s10, 0x5800
	s_addc_u32 s11, s11, 0
	s_add_u32 s12, s12, 0x5800
	s_addc_u32 s13, s13, 0
	s_add_u32 s14, s14, 0x5800
	s_addc_u32 s15, s15, 0
	s_add_u32 s16, s16, 0x5800
	s_addc_u32 s17, s17, 0
	s_add_u32 s18, s18, 0x5800
	s_addc_u32 s19, s19, 0
	global_load_dword v192, v1, s[8:9]
	global_load_dword v193, v2, s[8:9]
	global_load_dword v194, v1, s[10:11]
	global_load_dword v195, v2, s[10:11]
	global_load_dword v196, v1, s[12:13]
	global_load_dword v197, v2, s[12:13]
	global_load_dword v198, v1, s[14:15]
	global_load_dword v199, v2, s[14:15]
	global_load_dword v200, v1, s[16:17]
	global_load_dword v201, v2, s[16:17]
	global_load_dword v202, v1, s[18:19]
	global_load_dword v203, v2, s[18:19]
	s_add_u32 s8, s8, 0x5800
	s_addc_u32 s9, s9, 0
	s_add_u32 s10, s10, 0x5800
	s_addc_u32 s11, s11, 0
	s_add_u32 s12, s12, 0x5800
	s_addc_u32 s13, s13, 0
	s_add_u32 s14, s14, 0x5800
	s_addc_u32 s15, s15, 0
	s_add_u32 s16, s16, 0x5800
	s_addc_u32 s17, s17, 0
	s_add_u32 s18, s18, 0x5800
	s_addc_u32 s19, s19, 0
	s_mov_b32 s32, 0
.Lffn_p9_loop_lat1:
	s_cmp_eq_u32 s32, 7
	s_cselect_b32 s42, s31, -1
	s_cmp_lg_u32 s32, 0
	s_cbranch_scc1 .Lffn_p9_wn3
	s_waitcnt vmcnt(24)
	s_branch .Lffn_p9_we2
.Lffn_p9_wn3:
	s_waitcnt vmcnt(32)
.Lffn_p9_we2:
	v_and_b32_e32 v156, s28, v156
	v_and_b32_e32 v157, s28, v157
	v_lshlrev_b32_e32 v98, 16, v156
	v_and_b32_e32 v99, 0xffff0000, v156
	v_lshlrev_b32_e32 v100, 16, v157
	v_and_b32_e32 v101, 0xffff0000, v157
	v_lshlrev_b32_e32 v102, 16, v158
	v_and_b32_e32 v103, 0xffff0000, v158
	v_lshlrev_b32_e32 v104, 16, v159
	v_and_b32_e32 v105, 0xffff0000, v159
	v_lshlrev_b32_e32 v106, 16, v160
	v_and_b32_e32 v107, 0xffff0000, v160
	v_lshlrev_b32_e32 v108, 16, v161
	v_and_b32_e32 v109, 0xffff0000, v161
	v_lshlrev_b32_e32 v110, 16, v162
	v_and_b32_e32 v111, 0xffff0000, v162
	v_lshlrev_b32_e32 v112, 16, v163
	v_and_b32_e32 v113, 0xffff0000, v163
	v_lshlrev_b32_e32 v114, 16, v164
	v_and_b32_e32 v115, 0xffff0000, v164
	v_lshlrev_b32_e32 v116, 16, v165
	v_and_b32_e32 v117, 0xffff0000, v165
	v_and_b32_e32 v166, s29, v166
	v_and_b32_e32 v167, s29, v167
	v_lshlrev_b32_e32 v118, 16, v166
	v_and_b32_e32 v119, 0xffff0000, v166
	v_lshlrev_b32_e32 v120, 16, v167
	v_and_b32_e32 v121, 0xffff0000, v167
	v_pk_fma_f32 v[146:147], v[10:11], v[50:51], v[46:47]
	v_pk_fma_f32 v[148:149], v[28:29], v[52:53], v[48:49]
	v_pk_fma_f32 v[146:147], v[12:13], v[74:75], v[146:147]
	v_pk_fma_f32 v[148:149], v[30:31], v[76:77], v[148:149]
	v_pk_fma_f32 v[146:147], v[14:15], v[98:99], v[146:147]
	v_pk_fma_f32 v[148:149], v[32:33], v[100:101], v[148:149]
	v_pk_fma_f32 v[146:147], v[16:17], v[54:55], v[146:147]
	v_pk_fma_f32 v[148:149], v[34:35], v[56:57], v[148:149]
	v_pk_fma_f32 v[146:147], v[18:19], v[78:79], v[146:147]
	v_pk_fma_f32 v[148:149], v[36:37], v[80:81], v[148:149]
	v_pk_fma_f32 v[146:147], v[20:21], v[102:103], v[146:147]
	v_pk_fma_f32 v[148:149], v[38:39], v[104:105], v[148:149]
	v_pk_fma_f32 v[146:147], v[22:23], v[58:59], v[146:147]
	v_pk_fma_f32 v[148:149], v[40:41], v[60:61], v[148:149]
	v_pk_fma_f32 v[146:147], v[24:25], v[82:83], v[146:147]
	v_pk_fma_f32 v[148:149], v[42:43], v[84:85], v[148:149]
	v_pk_fma_f32 v[146:147], v[26:27], v[106:107], v[146:147]
	v_pk_fma_f32 v[148:149], v[44:45], v[108:109], v[148:149]
	v_pk_mul_f32 v[150:151], v[146:147], v[4:5]
	v_exp_f32_e32 v150, v150
	v_exp_f32_e32 v151, v151
	s_nop 0
	v_pk_add_f32 v[150:151], v[150:151], v[6:7]
	v_rcp_f32_e32 v150, v150
	v_rcp_f32_e32 v151, v151
	s_nop 0
	v_pk_mul_f32 v[150:151], v[150:151], v[146:147]
	v_pk_mul_f32 v[150:151], v[150:151], v[148:149]
	v_cvt_pk_bf16_f32 v204, v150, v151
	global_store_dword v1, v204, s[20:21]
	v_pk_fma_f32 v[146:147], v[10:11], v[54:55], v[46:47]
	v_pk_fma_f32 v[148:149], v[28:29], v[56:57], v[48:49]
	v_pk_fma_f32 v[146:147], v[12:13], v[78:79], v[146:147]
	v_pk_fma_f32 v[148:149], v[30:31], v[80:81], v[148:149]
	v_pk_fma_f32 v[146:147], v[14:15], v[102:103], v[146:147]
	v_pk_fma_f32 v[148:149], v[32:33], v[104:105], v[148:149]
	v_pk_fma_f32 v[146:147], v[16:17], v[58:59], v[146:147]
	v_pk_fma_f32 v[148:149], v[34:35], v[60:61], v[148:149]
	v_pk_fma_f32 v[146:147], v[18:19], v[82:83], v[146:147]
	v_pk_fma_f32 v[148:149], v[36:37], v[84:85], v[148:149]
	v_pk_fma_f32 v[146:147], v[20:21], v[106:107], v[146:147]
	v_pk_fma_f32 v[148:149], v[38:39], v[108:109], v[148:149]
	v_pk_fma_f32 v[146:147], v[22:23], v[62:63], v[146:147]
	v_pk_fma_f32 v[148:149], v[40:41], v[64:65], v[148:149]
	v_pk_fma_f32 v[146:147], v[24:25], v[86:87], v[146:147]
	v_pk_fma_f32 v[148:149], v[42:43], v[88:89], v[148:149]
	v_pk_fma_f32 v[146:147], v[26:27], v[110:111], v[146:147]
	v_pk_fma_f32 v[148:149], v[44:45], v[112:113], v[148:149]
	v_pk_mul_f32 v[150:151], v[146:147], v[4:5]
	v_exp_f32_e32 v150, v150
	v_exp_f32_e32 v151, v151
	s_nop 0
	v_pk_add_f32 v[150:151], v[150:151], v[6:7]
	v_rcp_f32_e32 v150, v150
	v_rcp_f32_e32 v151, v151
	s_nop 0
	v_pk_mul_f32 v[150:151], v[150:151], v[146:147]
	v_pk_mul_f32 v[150:151], v[150:151], v[148:149]
	v_cvt_pk_bf16_f32 v205, v150, v151
	global_store_dword v1, v205, s[22:23]
	v_pk_fma_f32 v[146:147], v[10:11], v[58:59], v[46:47]
	v_pk_fma_f32 v[148:149], v[28:29], v[60:61], v[48:49]
	v_pk_fma_f32 v[146:147], v[12:13], v[82:83], v[146:147]
	v_pk_fma_f32 v[148:149], v[30:31], v[84:85], v[148:149]
	v_pk_fma_f32 v[146:147], v[14:15], v[106:107], v[146:147]
	v_pk_fma_f32 v[148:149], v[32:33], v[108:109], v[148:149]
	v_pk_fma_f32 v[146:147], v[16:17], v[62:63], v[146:147]
	v_pk_fma_f32 v[148:149], v[34:35], v[64:65], v[148:149]
	v_pk_fma_f32 v[146:147], v[18:19], v[86:87], v[146:147]
	v_pk_fma_f32 v[148:149], v[36:37], v[88:89], v[148:149]
	v_pk_fma_f32 v[146:147], v[20:21], v[110:111], v[146:147]
	v_pk_fma_f32 v[148:149], v[38:39], v[112:113], v[148:149]
	v_pk_fma_f32 v[146:147], v[22:23], v[66:67], v[146:147]
	v_pk_fma_f32 v[148:149], v[40:41], v[68:69], v[148:149]
	v_pk_fma_f32 v[146:147], v[24:25], v[90:91], v[146:147]
	v_pk_fma_f32 v[148:149], v[42:43], v[92:93], v[148:149]
	v_pk_fma_f32 v[146:147], v[26:27], v[114:115], v[146:147]
	v_pk_fma_f32 v[148:149], v[44:45], v[116:117], v[148:149]
	v_pk_mul_f32 v[150:151], v[146:147], v[4:5]
	v_exp_f32_e32 v150, v150
	v_exp_f32_e32 v151, v151
	s_nop 0
	v_pk_add_f32 v[150:151], v[150:151], v[6:7]
	v_rcp_f32_e32 v150, v150
	v_rcp_f32_e32 v151, v151
	s_nop 0
	v_pk_mul_f32 v[150:151], v[150:151], v[146:147]
	v_pk_mul_f32 v[150:151], v[150:151], v[148:149]
	v_cvt_pk_bf16_f32 v206, v150, v151
	global_store_dword v1, v206, s[24:25]
	v_pk_fma_f32 v[146:147], v[10:11], v[62:63], v[46:47]
	v_pk_fma_f32 v[148:149], v[28:29], v[64:65], v[48:49]
	v_pk_fma_f32 v[146:147], v[12:13], v[86:87], v[146:147]
	v_pk_fma_f32 v[148:149], v[30:31], v[88:89], v[148:149]
	v_pk_fma_f32 v[146:147], v[14:15], v[110:111], v[146:147]
	v_pk_fma_f32 v[148:149], v[32:33], v[112:113], v[148:149]
	v_pk_fma_f32 v[146:147], v[16:17], v[66:67], v[146:147]
	v_pk_fma_f32 v[148:149], v[34:35], v[68:69], v[148:149]
	v_pk_fma_f32 v[146:147], v[18:19], v[90:91], v[146:147]
	v_pk_fma_f32 v[148:149], v[36:37], v[92:93], v[148:149]
	v_pk_fma_f32 v[146:147], v[20:21], v[114:115], v[146:147]
	v_pk_fma_f32 v[148:149], v[38:39], v[116:117], v[148:149]
	v_pk_fma_f32 v[146:147], v[22:23], v[70:71], v[146:147]
	v_pk_fma_f32 v[148:149], v[40:41], v[72:73], v[148:149]
	v_pk_fma_f32 v[146:147], v[24:25], v[94:95], v[146:147]
	v_pk_fma_f32 v[148:149], v[42:43], v[96:97], v[148:149]
	v_pk_fma_f32 v[146:147], v[26:27], v[118:119], v[146:147]
	v_pk_fma_f32 v[148:149], v[44:45], v[120:121], v[148:149]
	v_pk_mul_f32 v[150:151], v[146:147], v[4:5]
	v_exp_f32_e32 v150, v150
	v_exp_f32_e32 v151, v151
	s_nop 0
	v_pk_add_f32 v[150:151], v[150:151], v[6:7]
	v_rcp_f32_e32 v150, v150
	v_rcp_f32_e32 v151, v151
	s_nop 0
	v_pk_mul_f32 v[150:151], v[150:151], v[146:147]
	v_pk_mul_f32 v[150:151], v[150:151], v[148:149]
	v_cvt_pk_bf16_f32 v207, v150, v151
	global_store_dword v1, v207, s[26:27]
	s_add_u32 s20, s20, 0x2c00
	s_addc_u32 s21, s21, 0
	s_add_u32 s22, s22, 0x2c00
	s_addc_u32 s23, s23, 0
	s_add_u32 s24, s24, 0x2c00
	s_addc_u32 s25, s25, 0
	s_add_u32 s26, s26, 0x2c00
	s_addc_u32 s27, s27, 0
	v_and_b32_e32 v168, s28, v168
	v_and_b32_e32 v169, s28, v169
	v_lshlrev_b32_e32 v122, 16, v168
	v_and_b32_e32 v123, 0xffff0000, v168
	v_lshlrev_b32_e32 v124, 16, v169
	v_and_b32_e32 v125, 0xffff0000, v169
	v_lshlrev_b32_e32 v126, 16, v170
	v_and_b32_e32 v127, 0xffff0000, v170
	v_lshlrev_b32_e32 v128, 16, v171
	v_and_b32_e32 v129, 0xffff0000, v171
	v_lshlrev_b32_e32 v130, 16, v172
	v_and_b32_e32 v131, 0xffff0000, v172
	v_lshlrev_b32_e32 v132, 16, v173
	v_and_b32_e32 v133, 0xffff0000, v173
	v_lshlrev_b32_e32 v134, 16, v174
	v_and_b32_e32 v135, 0xffff0000, v174
	v_lshlrev_b32_e32 v136, 16, v175
	v_and_b32_e32 v137, 0xffff0000, v175
	v_lshlrev_b32_e32 v138, 16, v176
	v_and_b32_e32 v139, 0xffff0000, v176
	v_lshlrev_b32_e32 v140, 16, v177
	v_and_b32_e32 v141, 0xffff0000, v177
	v_and_b32_e32 v178, s29, v178
	v_and_b32_e32 v179, s29, v179
	v_lshlrev_b32_e32 v142, 16, v178
	v_and_b32_e32 v143, 0xffff0000, v178
	v_lshlrev_b32_e32 v144, 16, v179
	v_and_b32_e32 v145, 0xffff0000, v179
	v_pk_fma_f32 v[146:147], v[10:11], v[74:75], v[46:47]
	v_pk_fma_f32 v[148:149], v[28:29], v[76:77], v[48:49]
	v_pk_fma_f32 v[146:147], v[12:13], v[98:99], v[146:147]
	v_pk_fma_f32 v[148:149], v[30:31], v[100:101], v[148:149]
	v_pk_fma_f32 v[146:147], v[14:15], v[122:123], v[146:147]
	v_pk_fma_f32 v[148:149], v[32:33], v[124:125], v[148:149]
	v_pk_fma_f32 v[146:147], v[16:17], v[78:79], v[146:147]
	v_pk_fma_f32 v[148:149], v[34:35], v[80:81], v[148:149]
	v_pk_fma_f32 v[146:147], v[18:19], v[102:103], v[146:147]
	v_pk_fma_f32 v[148:149], v[36:37], v[104:105], v[148:149]
	v_pk_fma_f32 v[146:147], v[20:21], v[126:127], v[146:147]
	v_pk_fma_f32 v[148:149], v[38:39], v[128:129], v[148:149]
	v_pk_fma_f32 v[146:147], v[22:23], v[82:83], v[146:147]
	v_pk_fma_f32 v[148:149], v[40:41], v[84:85], v[148:149]
	v_pk_fma_f32 v[146:147], v[24:25], v[106:107], v[146:147]
	v_pk_fma_f32 v[148:149], v[42:43], v[108:109], v[148:149]
	v_pk_fma_f32 v[146:147], v[26:27], v[130:131], v[146:147]
	v_pk_fma_f32 v[148:149], v[44:45], v[132:133], v[148:149]
	v_pk_mul_f32 v[150:151], v[146:147], v[4:5]
	v_exp_f32_e32 v150, v150
	v_exp_f32_e32 v151, v151
	s_nop 0
	v_pk_add_f32 v[150:151], v[150:151], v[6:7]
	v_rcp_f32_e32 v150, v150
	v_rcp_f32_e32 v151, v151
	s_nop 0
	v_pk_mul_f32 v[150:151], v[150:151], v[146:147]
	v_pk_mul_f32 v[150:151], v[150:151], v[148:149]
	v_cvt_pk_bf16_f32 v204, v150, v151
	global_store_dword v1, v204, s[20:21]
	v_pk_fma_f32 v[146:147], v[10:11], v[78:79], v[46:47]
	v_pk_fma_f32 v[148:149], v[28:29], v[80:81], v[48:49]
	v_pk_fma_f32 v[146:147], v[12:13], v[102:103], v[146:147]
	v_pk_fma_f32 v[148:149], v[30:31], v[104:105], v[148:149]
	v_pk_fma_f32 v[146:147], v[14:15], v[126:127], v[146:147]
	v_pk_fma_f32 v[148:149], v[32:33], v[128:129], v[148:149]
	v_pk_fma_f32 v[146:147], v[16:17], v[82:83], v[146:147]
	v_pk_fma_f32 v[148:149], v[34:35], v[84:85], v[148:149]
	v_pk_fma_f32 v[146:147], v[18:19], v[106:107], v[146:147]
	v_pk_fma_f32 v[148:149], v[36:37], v[108:109], v[148:149]
	v_pk_fma_f32 v[146:147], v[20:21], v[130:131], v[146:147]
	v_pk_fma_f32 v[148:149], v[38:39], v[132:133], v[148:149]
	v_pk_fma_f32 v[146:147], v[22:23], v[86:87], v[146:147]
	v_pk_fma_f32 v[148:149], v[40:41], v[88:89], v[148:149]
	v_pk_fma_f32 v[146:147], v[24:25], v[110:111], v[146:147]
	v_pk_fma_f32 v[148:149], v[42:43], v[112:113], v[148:149]
	v_pk_fma_f32 v[146:147], v[26:27], v[134:135], v[146:147]
	v_pk_fma_f32 v[148:149], v[44:45], v[136:137], v[148:149]
	v_pk_mul_f32 v[150:151], v[146:147], v[4:5]
	v_exp_f32_e32 v150, v150
	v_exp_f32_e32 v151, v151
	s_nop 0
	v_pk_add_f32 v[150:151], v[150:151], v[6:7]
	v_rcp_f32_e32 v150, v150
	v_rcp_f32_e32 v151, v151
	s_nop 0
	v_pk_mul_f32 v[150:151], v[150:151], v[146:147]
	v_pk_mul_f32 v[150:151], v[150:151], v[148:149]
	v_cvt_pk_bf16_f32 v205, v150, v151
	global_store_dword v1, v205, s[22:23]
	v_pk_fma_f32 v[146:147], v[10:11], v[82:83], v[46:47]
	v_pk_fma_f32 v[148:149], v[28:29], v[84:85], v[48:49]
	v_pk_fma_f32 v[146:147], v[12:13], v[106:107], v[146:147]
	v_pk_fma_f32 v[148:149], v[30:31], v[108:109], v[148:149]
	v_pk_fma_f32 v[146:147], v[14:15], v[130:131], v[146:147]
	v_pk_fma_f32 v[148:149], v[32:33], v[132:133], v[148:149]
	v_pk_fma_f32 v[146:147], v[16:17], v[86:87], v[146:147]
	v_pk_fma_f32 v[148:149], v[34:35], v[88:89], v[148:149]
	v_pk_fma_f32 v[146:147], v[18:19], v[110:111], v[146:147]
	v_pk_fma_f32 v[148:149], v[36:37], v[112:113], v[148:149]
	v_pk_fma_f32 v[146:147], v[20:21], v[134:135], v[146:147]
	v_pk_fma_f32 v[148:149], v[38:39], v[136:137], v[148:149]
	v_pk_fma_f32 v[146:147], v[22:23], v[90:91], v[146:147]
	v_pk_fma_f32 v[148:149], v[40:41], v[92:93], v[148:149]
	v_pk_fma_f32 v[146:147], v[24:25], v[114:115], v[146:147]
	v_pk_fma_f32 v[148:149], v[42:43], v[116:117], v[148:149]
	v_pk_fma_f32 v[146:147], v[26:27], v[138:139], v[146:147]
	v_pk_fma_f32 v[148:149], v[44:45], v[140:141], v[148:149]
	v_pk_mul_f32 v[150:151], v[146:147], v[4:5]
	v_exp_f32_e32 v150, v150
	v_exp_f32_e32 v151, v151
	s_nop 0
	v_pk_add_f32 v[150:151], v[150:151], v[6:7]
	v_rcp_f32_e32 v150, v150
	v_rcp_f32_e32 v151, v151
	s_nop 0
	v_pk_mul_f32 v[150:151], v[150:151], v[146:147]
	v_pk_mul_f32 v[150:151], v[150:151], v[148:149]
	v_cvt_pk_bf16_f32 v206, v150, v151
	global_store_dword v1, v206, s[24:25]
	v_pk_fma_f32 v[146:147], v[10:11], v[86:87], v[46:47]
	v_pk_fma_f32 v[148:149], v[28:29], v[88:89], v[48:49]
	v_pk_fma_f32 v[146:147], v[12:13], v[110:111], v[146:147]
	v_pk_fma_f32 v[148:149], v[30:31], v[112:113], v[148:149]
	v_pk_fma_f32 v[146:147], v[14:15], v[134:135], v[146:147]
	v_pk_fma_f32 v[148:149], v[32:33], v[136:137], v[148:149]
	v_pk_fma_f32 v[146:147], v[16:17], v[90:91], v[146:147]
	v_pk_fma_f32 v[148:149], v[34:35], v[92:93], v[148:149]
	v_pk_fma_f32 v[146:147], v[18:19], v[114:115], v[146:147]
	v_pk_fma_f32 v[148:149], v[36:37], v[116:117], v[148:149]
	v_pk_fma_f32 v[146:147], v[20:21], v[138:139], v[146:147]
	v_pk_fma_f32 v[148:149], v[38:39], v[140:141], v[148:149]
	v_pk_fma_f32 v[146:147], v[22:23], v[94:95], v[146:147]
	v_pk_fma_f32 v[148:149], v[40:41], v[96:97], v[148:149]
	v_pk_fma_f32 v[146:147], v[24:25], v[118:119], v[146:147]
	v_pk_fma_f32 v[148:149], v[42:43], v[120:121], v[148:149]
	v_pk_fma_f32 v[146:147], v[26:27], v[142:143], v[146:147]
	v_pk_fma_f32 v[148:149], v[44:45], v[144:145], v[148:149]
	v_pk_mul_f32 v[150:151], v[146:147], v[4:5]
	v_exp_f32_e32 v150, v150
	v_exp_f32_e32 v151, v151
	s_nop 0
	v_pk_add_f32 v[150:151], v[150:151], v[6:7]
	v_rcp_f32_e32 v150, v150
	v_rcp_f32_e32 v151, v151
	s_nop 0
	v_pk_mul_f32 v[150:151], v[150:151], v[146:147]
	v_pk_mul_f32 v[150:151], v[150:151], v[148:149]
	v_cvt_pk_bf16_f32 v207, v150, v151
	global_store_dword v1, v207, s[26:27]
	s_add_u32 s20, s20, 0x2c00
	s_addc_u32 s21, s21, 0
	s_add_u32 s22, s22, 0x2c00
	s_addc_u32 s23, s23, 0
	s_add_u32 s24, s24, 0x2c00
	s_addc_u32 s25, s25, 0
	s_add_u32 s26, s26, 0x2c00
	s_addc_u32 s27, s27, 0
	s_cmp_eq_u32 s32, 7
	s_cbranch_scc1 .Lffn_p9_skipld4
	global_load_dword v156, v1, s[8:9]
	global_load_dword v157, v2, s[8:9]
	global_load_dword v158, v1, s[10:11]
	global_load_dword v159, v2, s[10:11]
	global_load_dword v160, v1, s[12:13]
	global_load_dword v161, v2, s[12:13]
	global_load_dword v162, v1, s[14:15]
	global_load_dword v163, v2, s[14:15]
	global_load_dword v164, v1, s[16:17]
	global_load_dword v165, v2, s[16:17]
	global_load_dword v166, v1, s[18:19]
	global_load_dword v167, v2, s[18:19]
	s_add_u32 s8, s8, 0x5800
	s_addc_u32 s9, s9, 0
	s_add_u32 s10, s10, 0x5800
	s_addc_u32 s11, s11, 0
	s_add_u32 s12, s12, 0x5800
	s_addc_u32 s13, s13, 0
	s_add_u32 s14, s14, 0x5800
	s_addc_u32 s15, s15, 0
	s_add_u32 s16, s16, 0x5800
	s_addc_u32 s17, s17, 0
	s_add_u32 s18, s18, 0x5800
	s_addc_u32 s19, s19, 0
	global_load_dword v168, v1, s[8:9]
	global_load_dword v169, v2, s[8:9]
	global_load_dword v170, v1, s[10:11]
	global_load_dword v171, v2, s[10:11]
	global_load_dword v172, v1, s[12:13]
	global_load_dword v173, v2, s[12:13]
	global_load_dword v174, v1, s[14:15]
	global_load_dword v175, v2, s[14:15]
	global_load_dword v176, v1, s[16:17]
	global_load_dword v177, v2, s[16:17]
	global_load_dword v178, v1, s[18:19]
	global_load_dword v179, v2, s[18:19]
	s_add_u32 s8, s8, 0x5800
	s_addc_u32 s9, s9, 0
	s_add_u32 s10, s10, 0x5800
	s_addc_u32 s11, s11, 0
	s_add_u32 s12, s12, 0x5800
	s_addc_u32 s13, s13, 0
	s_add_u32 s14, s14, 0x5800
	s_addc_u32 s15, s15, 0
	s_add_u32 s16, s16, 0x5800
	s_addc_u32 s17, s17, 0
	s_add_u32 s18, s18, 0x5800
	s_addc_u32 s19, s19, 0
.Lffn_p9_skipld4:
	s_cmp_lg_u32 s32, 7
	s_cbranch_scc1 .Lffn_p9_wn6
	s_waitcnt vmcnt(8)
	s_branch .Lffn_p9_we5

.Lffn_p9_we5:
	v_and_b32_e32 v180, s28, v180
	v_and_b32_e32 v181, s28, v181
	v_lshlrev_b32_e32 v50, 16, v180
	v_and_b32_e32 v51, 0xffff0000, v180
	v_lshlrev_b32_e32 v52, 16, v181
	v_and_b32_e32 v53, 0xffff0000, v181
	v_lshlrev_b32_e32 v54, 16, v182
	v_and_b32_e32 v55, 0xffff0000, v182
	v_lshlrev_b32_e32 v56, 16, v183
	v_and_b32_e32 v57, 0xffff0000, v183
	v_lshlrev_b32_e32 v58, 16, v184
	v_and_b32_e32 v59, 0xffff0000, v184
	v_lshlrev_b32_e32 v60, 16, v185
	v_and_b32_e32 v61, 0xffff0000, v185
	v_lshlrev_b32_e32 v62, 16, v186
	v_and_b32_e32 v63, 0xffff0000, v186
	v_lshlrev_b32_e32 v64, 16, v187
	v_and_b32_e32 v65, 0xffff0000, v187
	v_lshlrev_b32_e32 v66, 16, v188
	v_and_b32_e32 v67, 0xffff0000, v188
	v_lshlrev_b32_e32 v68, 16, v189
	v_and_b32_e32 v69, 0xffff0000, v189
	v_and_b32_e32 v190, s29, v190
	v_and_b32_e32 v191, s29, v191
	v_lshlrev_b32_e32 v70, 16, v190
	v_and_b32_e32 v71, 0xffff0000, v190
	v_lshlrev_b32_e32 v72, 16, v191
	v_and_b32_e32 v73, 0xffff0000, v191
	v_pk_fma_f32 v[146:147], v[10:11], v[98:99], v[46:47]
	v_pk_fma_f32 v[148:149], v[28:29], v[100:101], v[48:49]
	v_pk_fma_f32 v[146:147], v[12:13], v[122:123], v[146:147]
	v_pk_fma_f32 v[148:149], v[30:31], v[124:125], v[148:149]
	v_pk_fma_f32 v[146:147], v[14:15], v[50:51], v[146:147]
	v_pk_fma_f32 v[148:149], v[32:33], v[52:53], v[148:149]
	v_pk_fma_f32 v[146:147], v[16:17], v[102:103], v[146:147]
	v_pk_fma_f32 v[148:149], v[34:35], v[104:105], v[148:149]
	v_pk_fma_f32 v[146:147], v[18:19], v[126:127], v[146:147]
	v_pk_fma_f32 v[148:149], v[36:37], v[128:129], v[148:149]
	v_pk_fma_f32 v[146:147], v[20:21], v[54:55], v[146:147]
	v_pk_fma_f32 v[148:149], v[38:39], v[56:57], v[148:149]
	v_pk_fma_f32 v[146:147], v[22:23], v[106:107], v[146:147]
	v_pk_fma_f32 v[148:149], v[40:41], v[108:109], v[148:149]
	v_pk_fma_f32 v[146:147], v[24:25], v[130:131], v[146:147]
	v_pk_fma_f32 v[148:149], v[42:43], v[132:133], v[148:149]
	v_pk_fma_f32 v[146:147], v[26:27], v[58:59], v[146:147]
	v_pk_fma_f32 v[148:149], v[44:45], v[60:61], v[148:149]
	v_pk_mul_f32 v[150:151], v[146:147], v[4:5]
	v_exp_f32_e32 v150, v150
	v_exp_f32_e32 v151, v151
	s_nop 0
	v_pk_add_f32 v[150:151], v[150:151], v[6:7]
	v_rcp_f32_e32 v150, v150
	v_rcp_f32_e32 v151, v151
	s_nop 0
	v_pk_mul_f32 v[150:151], v[150:151], v[146:147]
	v_pk_mul_f32 v[150:151], v[150:151], v[148:149]
	v_cvt_pk_bf16_f32 v204, v150, v151
	global_store_dword v1, v204, s[20:21]
	v_pk_fma_f32 v[146:147], v[10:11], v[102:103], v[46:47]
	v_pk_fma_f32 v[148:149], v[28:29], v[104:105], v[48:49]
	v_pk_fma_f32 v[146:147], v[12:13], v[126:127], v[146:147]
	v_pk_fma_f32 v[148:149], v[30:31], v[128:129], v[148:149]
	v_pk_fma_f32 v[146:147], v[14:15], v[54:55], v[146:147]
	v_pk_fma_f32 v[148:149], v[32:33], v[56:57], v[148:149]
	v_pk_fma_f32 v[146:147], v[16:17], v[106:107], v[146:147]
	v_pk_fma_f32 v[148:149], v[34:35], v[108:109], v[148:149]
	v_pk_fma_f32 v[146:147], v[18:19], v[130:131], v[146:147]
	v_pk_fma_f32 v[148:149], v[36:37], v[132:133], v[148:149]
	v_pk_fma_f32 v[146:147], v[20:21], v[58:59], v[146:147]
	v_pk_fma_f32 v[148:149], v[38:39], v[60:61], v[148:149]
	v_pk_fma_f32 v[146:147], v[22:23], v[110:111], v[146:147]
	v_pk_fma_f32 v[148:149], v[40:41], v[112:113], v[148:149]
	v_pk_fma_f32 v[146:147], v[24:25], v[134:135], v[146:147]
	v_pk_fma_f32 v[148:149], v[42:43], v[136:137], v[148:149]
	v_pk_fma_f32 v[146:147], v[26:27], v[62:63], v[146:147]
	v_pk_fma_f32 v[148:149], v[44:45], v[64:65], v[148:149]
	v_pk_mul_f32 v[150:151], v[146:147], v[4:5]
	v_exp_f32_e32 v150, v150
	v_exp_f32_e32 v151, v151
	s_nop 0
	v_pk_add_f32 v[150:151], v[150:151], v[6:7]
	v_rcp_f32_e32 v150, v150
	v_rcp_f32_e32 v151, v151
	s_nop 0
	v_pk_mul_f32 v[150:151], v[150:151], v[146:147]
	v_pk_mul_f32 v[150:151], v[150:151], v[148:149]
	v_cvt_pk_bf16_f32 v205, v150, v151
	global_store_dword v1, v205, s[22:23]
	v_pk_fma_f32 v[146:147], v[10:11], v[106:107], v[46:47]
	v_pk_fma_f32 v[148:149], v[28:29], v[108:109], v[48:49]
	v_pk_fma_f32 v[146:147], v[12:13], v[130:131], v[146:147]
	v_pk_fma_f32 v[148:149], v[30:31], v[132:133], v[148:149]
	v_pk_fma_f32 v[146:147], v[14:15], v[58:59], v[146:147]
	v_pk_fma_f32 v[148:149], v[32:33], v[60:61], v[148:149]
	v_pk_fma_f32 v[146:147], v[16:17], v[110:111], v[146:147]
	v_pk_fma_f32 v[148:149], v[34:35], v[112:113], v[148:149]
	v_pk_fma_f32 v[146:147], v[18:19], v[134:135], v[146:147]
	v_pk_fma_f32 v[148:149], v[36:37], v[136:137], v[148:149]
	v_pk_fma_f32 v[146:147], v[20:21], v[62:63], v[146:147]
	v_pk_fma_f32 v[148:149], v[38:39], v[64:65], v[148:149]
	v_pk_fma_f32 v[146:147], v[22:23], v[114:115], v[146:147]
	v_pk_fma_f32 v[148:149], v[40:41], v[116:117], v[148:149]
	v_pk_fma_f32 v[146:147], v[24:25], v[138:139], v[146:147]
	v_pk_fma_f32 v[148:149], v[42:43], v[140:141], v[148:149]
	v_pk_fma_f32 v[146:147], v[26:27], v[66:67], v[146:147]
	v_pk_fma_f32 v[148:149], v[44:45], v[68:69], v[148:149]
	v_pk_mul_f32 v[150:151], v[146:147], v[4:5]
	v_exp_f32_e32 v150, v150
	v_exp_f32_e32 v151, v151
	s_nop 0
	v_pk_add_f32 v[150:151], v[150:151], v[6:7]
	v_rcp_f32_e32 v150, v150
	v_rcp_f32_e32 v151, v151
	s_nop 0
	v_pk_mul_f32 v[150:151], v[150:151], v[146:147]
	v_pk_mul_f32 v[150:151], v[150:151], v[148:149]
	v_cvt_pk_bf16_f32 v206, v150, v151
	global_store_dword v1, v206, s[24:25]
	v_pk_fma_f32 v[146:147], v[10:11], v[110:111], v[46:47]
	v_pk_fma_f32 v[148:149], v[28:29], v[112:113], v[48:49]
	v_pk_fma_f32 v[146:147], v[12:13], v[134:135], v[146:147]
	v_pk_fma_f32 v[148:149], v[30:31], v[136:137], v[148:149]
	v_pk_fma_f32 v[146:147], v[14:15], v[62:63], v[146:147]
	v_pk_fma_f32 v[148:149], v[32:33], v[64:65], v[148:149]
	v_pk_fma_f32 v[146:147], v[16:17], v[114:115], v[146:147]
	v_pk_fma_f32 v[148:149], v[34:35], v[116:117], v[148:149]
	v_pk_fma_f32 v[146:147], v[18:19], v[138:139], v[146:147]
	v_pk_fma_f32 v[148:149], v[36:37], v[140:141], v[148:149]
	v_pk_fma_f32 v[146:147], v[20:21], v[66:67], v[146:147]
	v_pk_fma_f32 v[148:149], v[38:39], v[68:69], v[148:149]
	v_pk_fma_f32 v[146:147], v[22:23], v[118:119], v[146:147]
	v_pk_fma_f32 v[148:149], v[40:41], v[120:121], v[148:149]
	v_pk_fma_f32 v[146:147], v[24:25], v[142:143], v[146:147]
	v_pk_fma_f32 v[148:149], v[42:43], v[144:145], v[148:149]
	v_pk_fma_f32 v[146:147], v[26:27], v[70:71], v[146:147]
	v_pk_fma_f32 v[148:149], v[44:45], v[72:73], v[148:149]
	v_pk_mul_f32 v[150:151], v[146:147], v[4:5]
	v_exp_f32_e32 v150, v150
	v_exp_f32_e32 v151, v151
	s_nop 0
	v_pk_add_f32 v[150:151], v[150:151], v[6:7]
	v_rcp_f32_e32 v150, v150
	v_rcp_f32_e32 v151, v151
	s_nop 0
	v_pk_mul_f32 v[150:151], v[150:151], v[146:147]
	v_pk_mul_f32 v[150:151], v[150:151], v[148:149]
	v_cvt_pk_bf16_f32 v207, v150, v151
	global_store_dword v1, v207, s[26:27]
	s_add_u32 s20, s20, 0x2c00
	s_addc_u32 s21, s21, 0
	s_add_u32 s22, s22, 0x2c00
	s_addc_u32 s23, s23, 0
	s_add_u32 s24, s24, 0x2c00
	s_addc_u32 s25, s25, 0
	s_add_u32 s26, s26, 0x2c00
	s_addc_u32 s27, s27, 0
	v_and_b32_e32 v192, s42, v192
	v_and_b32_e32 v193, s42, v193
	v_and_b32_e32 v192, s28, v192
	v_and_b32_e32 v193, s28, v193
	v_lshlrev_b32_e32 v74, 16, v192
	v_and_b32_e32 v75, 0xffff0000, v192
	v_lshlrev_b32_e32 v76, 16, v193
	v_and_b32_e32 v77, 0xffff0000, v193
	v_and_b32_e32 v194, s42, v194
	v_and_b32_e32 v195, s42, v195
	v_lshlrev_b32_e32 v78, 16, v194
	v_and_b32_e32 v79, 0xffff0000, v194
	v_lshlrev_b32_e32 v80, 16, v195
	v_and_b32_e32 v81, 0xffff0000, v195
	v_and_b32_e32 v196, s42, v196
	v_and_b32_e32 v197, s42, v197
	v_lshlrev_b32_e32 v82, 16, v196
	v_and_b32_e32 v83, 0xffff0000, v196
	v_lshlrev_b32_e32 v84, 16, v197
	v_and_b32_e32 v85, 0xffff0000, v197
	v_and_b32_e32 v198, s42, v198
	v_and_b32_e32 v199, s42, v199
	v_lshlrev_b32_e32 v86, 16, v198
	v_and_b32_e32 v87, 0xffff0000, v198
	v_lshlrev_b32_e32 v88, 16, v199
	v_and_b32_e32 v89, 0xffff0000, v199
	v_and_b32_e32 v200, s42, v200
	v_and_b32_e32 v201, s42, v201
	v_lshlrev_b32_e32 v90, 16, v200
	v_and_b32_e32 v91, 0xffff0000, v200
	v_lshlrev_b32_e32 v92, 16, v201
	v_and_b32_e32 v93, 0xffff0000, v201
	v_and_b32_e32 v202, s42, v202
	v_and_b32_e32 v203, s42, v203
	v_and_b32_e32 v202, s29, v202
	v_and_b32_e32 v203, s29, v203
	v_lshlrev_b32_e32 v94, 16, v202
	v_and_b32_e32 v95, 0xffff0000, v202
	v_lshlrev_b32_e32 v96, 16, v203
	v_and_b32_e32 v97, 0xffff0000, v203
	v_pk_fma_f32 v[146:147], v[10:11], v[122:123], v[46:47]
	v_pk_fma_f32 v[148:149], v[28:29], v[124:125], v[48:49]
	v_pk_fma_f32 v[146:147], v[12:13], v[50:51], v[146:147]
	v_pk_fma_f32 v[148:149], v[30:31], v[52:53], v[148:149]
	v_pk_fma_f32 v[146:147], v[14:15], v[74:75], v[146:147]
	v_pk_fma_f32 v[148:149], v[32:33], v[76:77], v[148:149]
	v_pk_fma_f32 v[146:147], v[16:17], v[126:127], v[146:147]
	v_pk_fma_f32 v[148:149], v[34:35], v[128:129], v[148:149]
	v_pk_fma_f32 v[146:147], v[18:19], v[54:55], v[146:147]
	v_pk_fma_f32 v[148:149], v[36:37], v[56:57], v[148:149]
	v_pk_fma_f32 v[146:147], v[20:21], v[78:79], v[146:147]
	v_pk_fma_f32 v[148:149], v[38:39], v[80:81], v[148:149]
	v_pk_fma_f32 v[146:147], v[22:23], v[130:131], v[146:147]
	v_pk_fma_f32 v[148:149], v[40:41], v[132:133], v[148:149]
	v_pk_fma_f32 v[146:147], v[24:25], v[58:59], v[146:147]
	v_pk_fma_f32 v[148:149], v[42:43], v[60:61], v[148:149]
	v_pk_fma_f32 v[146:147], v[26:27], v[82:83], v[146:147]
	v_pk_fma_f32 v[148:149], v[44:45], v[84:85], v[148:149]
	v_pk_mul_f32 v[150:151], v[146:147], v[4:5]
	v_exp_f32_e32 v150, v150
	v_exp_f32_e32 v151, v151
	s_nop 0
	v_pk_add_f32 v[150:151], v[150:151], v[6:7]
	v_rcp_f32_e32 v150, v150
	v_rcp_f32_e32 v151, v151
	s_nop 0
	v_pk_mul_f32 v[150:151], v[150:151], v[146:147]
	v_pk_mul_f32 v[150:151], v[150:151], v[148:149]
	v_cvt_pk_bf16_f32 v204, v150, v151
	global_store_dword v1, v204, s[20:21]
	v_pk_fma_f32 v[146:147], v[10:11], v[126:127], v[46:47]
	v_pk_fma_f32 v[148:149], v[28:29], v[128:129], v[48:49]
	v_pk_fma_f32 v[146:147], v[12:13], v[54:55], v[146:147]
	v_pk_fma_f32 v[148:149], v[30:31], v[56:57], v[148:149]
	v_pk_fma_f32 v[146:147], v[14:15], v[78:79], v[146:147]
	v_pk_fma_f32 v[148:149], v[32:33], v[80:81], v[148:149]
	v_pk_fma_f32 v[146:147], v[16:17], v[130:131], v[146:147]
	v_pk_fma_f32 v[148:149], v[34:35], v[132:133], v[148:149]
	v_pk_fma_f32 v[146:147], v[18:19], v[58:59], v[146:147]
	v_pk_fma_f32 v[148:149], v[36:37], v[60:61], v[148:149]
	v_pk_fma_f32 v[146:147], v[20:21], v[82:83], v[146:147]
	v_pk_fma_f32 v[148:149], v[38:39], v[84:85], v[148:149]
	v_pk_fma_f32 v[146:147], v[22:23], v[134:135], v[146:147]
	v_pk_fma_f32 v[148:149], v[40:41], v[136:137], v[148:149]
	v_pk_fma_f32 v[146:147], v[24:25], v[62:63], v[146:147]
	v_pk_fma_f32 v[148:149], v[42:43], v[64:65], v[148:149]
	v_pk_fma_f32 v[146:147], v[26:27], v[86:87], v[146:147]
	v_pk_fma_f32 v[148:149], v[44:45], v[88:89], v[148:149]
	v_pk_mul_f32 v[150:151], v[146:147], v[4:5]
	v_exp_f32_e32 v150, v150
	v_exp_f32_e32 v151, v151
	s_nop 0
	v_pk_add_f32 v[150:151], v[150:151], v[6:7]
	v_rcp_f32_e32 v150, v150
	v_rcp_f32_e32 v151, v151
	s_nop 0
	v_pk_mul_f32 v[150:151], v[150:151], v[146:147]
	v_pk_mul_f32 v[150:151], v[150:151], v[148:149]
	v_cvt_pk_bf16_f32 v205, v150, v151
	global_store_dword v1, v205, s[22:23]
	v_pk_fma_f32 v[146:147], v[10:11], v[130:131], v[46:47]
	v_pk_fma_f32 v[148:149], v[28:29], v[132:133], v[48:49]
	v_pk_fma_f32 v[146:147], v[12:13], v[58:59], v[146:147]
	v_pk_fma_f32 v[148:149], v[30:31], v[60:61], v[148:149]
	v_pk_fma_f32 v[146:147], v[14:15], v[82:83], v[146:147]
	v_pk_fma_f32 v[148:149], v[32:33], v[84:85], v[148:149]
	v_pk_fma_f32 v[146:147], v[16:17], v[134:135], v[146:147]
	v_pk_fma_f32 v[148:149], v[34:35], v[136:137], v[148:149]
	v_pk_fma_f32 v[146:147], v[18:19], v[62:63], v[146:147]
	v_pk_fma_f32 v[148:149], v[36:37], v[64:65], v[148:149]
	v_pk_fma_f32 v[146:147], v[20:21], v[86:87], v[146:147]
	v_pk_fma_f32 v[148:149], v[38:39], v[88:89], v[148:149]
	v_pk_fma_f32 v[146:147], v[22:23], v[138:139], v[146:147]
	v_pk_fma_f32 v[148:149], v[40:41], v[140:141], v[148:149]
	v_pk_fma_f32 v[146:147], v[24:25], v[66:67], v[146:147]
	v_pk_fma_f32 v[148:149], v[42:43], v[68:69], v[148:149]
	v_pk_fma_f32 v[146:147], v[26:27], v[90:91], v[146:147]
	v_pk_fma_f32 v[148:149], v[44:45], v[92:93], v[148:149]
	v_pk_mul_f32 v[150:151], v[146:147], v[4:5]
	v_exp_f32_e32 v150, v150
	v_exp_f32_e32 v151, v151
	s_nop 0
	v_pk_add_f32 v[150:151], v[150:151], v[6:7]
	v_rcp_f32_e32 v150, v150
	v_rcp_f32_e32 v151, v151
	s_nop 0
	v_pk_mul_f32 v[150:151], v[150:151], v[146:147]
	v_pk_mul_f32 v[150:151], v[150:151], v[148:149]
	v_cvt_pk_bf16_f32 v206, v150, v151
	global_store_dword v1, v206, s[24:25]
	v_pk_fma_f32 v[146:147], v[10:11], v[134:135], v[46:47]
	v_pk_fma_f32 v[148:149], v[28:29], v[136:137], v[48:49]
	v_pk_fma_f32 v[146:147], v[12:13], v[62:63], v[146:147]
	v_pk_fma_f32 v[148:149], v[30:31], v[64:65], v[148:149]
	v_pk_fma_f32 v[146:147], v[14:15], v[86:87], v[146:147]
	v_pk_fma_f32 v[148:149], v[32:33], v[88:89], v[148:149]
	v_pk_fma_f32 v[146:147], v[16:17], v[138:139], v[146:147]
	v_pk_fma_f32 v[148:149], v[34:35], v[140:141], v[148:149]
	v_pk_fma_f32 v[146:147], v[18:19], v[66:67], v[146:147]
	v_pk_fma_f32 v[148:149], v[36:37], v[68:69], v[148:149]
	v_pk_fma_f32 v[146:147], v[20:21], v[90:91], v[146:147]
	v_pk_fma_f32 v[148:149], v[38:39], v[92:93], v[148:149]
	v_pk_fma_f32 v[146:147], v[22:23], v[142:143], v[146:147]
	v_pk_fma_f32 v[148:149], v[40:41], v[144:145], v[148:149]
	v_pk_fma_f32 v[146:147], v[24:25], v[70:71], v[146:147]
	v_pk_fma_f32 v[148:149], v[42:43], v[72:73], v[148:149]
	v_pk_fma_f32 v[146:147], v[26:27], v[94:95], v[146:147]
	v_pk_fma_f32 v[148:149], v[44:45], v[96:97], v[148:149]
	v_pk_mul_f32 v[150:151], v[146:147], v[4:5]
	v_exp_f32_e32 v150, v150
	v_exp_f32_e32 v151, v151
	s_nop 0
	v_pk_add_f32 v[150:151], v[150:151], v[6:7]
	v_rcp_f32_e32 v150, v150
	v_rcp_f32_e32 v151, v151
	s_nop 0
	v_pk_mul_f32 v[150:151], v[150:151], v[146:147]
	v_pk_mul_f32 v[150:151], v[150:151], v[148:149]
	v_cvt_pk_bf16_f32 v207, v150, v151
	global_store_dword v1, v207, s[26:27]
	s_add_u32 s20, s20, 0x2c00
	s_addc_u32 s21, s21, 0
	s_add_u32 s22, s22, 0x2c00
	s_addc_u32 s23, s23, 0
	s_add_u32 s24, s24, 0x2c00
	s_addc_u32 s25, s25, 0
	s_add_u32 s26, s26, 0x2c00
	s_addc_u32 s27, s27, 0
	s_cmp_eq_u32 s32, 7
	s_cbranch_scc1 .Lffn_p9_skipld7
	global_load_dword v180, v1, s[8:9]
	global_load_dword v181, v2, s[8:9]
	global_load_dword v182, v1, s[10:11]
	global_load_dword v183, v2, s[10:11]
	global_load_dword v184, v1, s[12:13]
	global_load_dword v185, v2, s[12:13]
	global_load_dword v186, v1, s[14:15]
	global_load_dword v187, v2, s[14:15]
	global_load_dword v188, v1, s[16:17]
	global_load_dword v189, v2, s[16:17]
	global_load_dword v190, v1, s[18:19]
	global_load_dword v191, v2, s[18:19]
	s_add_u32 s8, s8, 0x5800
	s_addc_u32 s9, s9, 0
	s_add_u32 s10, s10, 0x5800
	s_addc_u32 s11, s11, 0
	s_add_u32 s12, s12, 0x5800
	s_addc_u32 s13, s13, 0
	s_add_u32 s14, s14, 0x5800
	s_addc_u32 s15, s15, 0
	s_add_u32 s16, s16, 0x5800
	s_addc_u32 s17, s17, 0
	s_add_u32 s18, s18, 0x5800
	s_addc_u32 s19, s19, 0
	global_load_dword v192, v1, s[8:9]
	global_load_dword v193, v2, s[8:9]
	global_load_dword v194, v1, s[10:11]
	global_load_dword v195, v2, s[10:11]
	global_load_dword v196, v1, s[12:13]
	global_load_dword v197, v2, s[12:13]
	global_load_dword v198, v1, s[14:15]
	global_load_dword v199, v2, s[14:15]
	global_load_dword v200, v1, s[16:17]
	global_load_dword v201, v2, s[16:17]
	global_load_dword v202, v1, s[18:19]
	global_load_dword v203, v2, s[18:19]
	s_add_u32 s8, s8, 0x5800
	s_addc_u32 s9, s9, 0
	s_add_u32 s10, s10, 0x5800
	s_addc_u32 s11, s11, 0
	s_add_u32 s12, s12, 0x5800
	s_addc_u32 s13, s13, 0
	s_add_u32 s14, s14, 0x5800
	s_addc_u32 s15, s15, 0
	s_add_u32 s16, s16, 0x5800
	s_addc_u32 s17, s17, 0
	s_add_u32 s18, s18, 0x5800
	s_addc_u32 s19, s19, 0
.Lffn_p9_skipld7:
	s_add_u32 s32, s32, 1
	s_cmp_lt_u32 s32, 8
	s_cbranch_scc1 .Lffn_p9_loop_lat1
	s_branch .Lffn_p9_itemend
.Lffn_p9_ctx:
	s_sub_u32 s35, s6, 1408
	s_mul_i32 s33, s35, 47663
	s_lshr_b32 s33, s33, 21
	s_mul_i32 s34, s33, 44
	s_sub_u32 s43, s35, s34
	s_and_b32 s34, s33, 1
	s_lshr_b32 s36, s33, 1
	s_mov_b32 s28, -1
	s_mov_b32 s29, -1
	s_cmp_lg_u32 s34, 0
	s_cselect_b32 s30, -1, 0
	s_cselect_b32 s31, 0, -1
	s_lshl_b32 s36, s36, 8
	s_lshl_b32 s34, s34, 7
	s_add_u32 s36, s36, s34
	v_and_b32_e32 v1, 63, v154
	v_lshlrev_b32_e32 v1, 2, v1
	s_lshl_b32 s33, s43, 8
	v_add_u32_e32 v1, s33, v1
	v_add_u32_e32 v2, 0x2c00, v1
	v_lshlrev_b32_e32 v3, 1, v1
	s_add_i32 s33, s36, 0
	s_mul_i32 s33, s33, 0x2c00
	s_add_u32 s20, s40, s33
	s_addc_u32 s21, s41, 0
	s_add_i32 s33, s36, -1
	s_mul_i32 s33, s33, 0x5800
	s_ashr_i32 s34, s33, 31
	s_add_u32 s8, s38, s33
	s_addc_u32 s9, s39, s34
	s_add_u32 s33, s0, 0x0
	s_addc_u32 s34, s1, 0
	s_mov_b32 s36, s33
	s_mov_b32 s37, s34
	global_load_dwordx2 v[10:11], v3, s[36:37]
	s_add_u32 s36, s36, 0x5800
	s_addc_u32 s37, s37, 0
	global_load_dwordx2 v[28:29], v3, s[36:37]
	s_add_u32 s33, s0, 0xb000
	s_addc_u32 s34, s1, 0
	s_mov_b32 s36, s33
	s_mov_b32 s37, s34
	global_load_dwordx2 v[12:13], v3, s[36:37]
	s_add_u32 s36, s36, 0x5800
	s_addc_u32 s37, s37, 0
	global_load_dwordx2 v[30:31], v3, s[36:37]
	s_add_u32 s33, s0, 0x16000
	s_addc_u32 s34, s1, 0
	s_mov_b32 s36, s33
	s_mov_b32 s37, s34
	global_load_dwordx2 v[14:15], v3, s[36:37]
	s_add_u32 s36, s36, 0x5800
	s_addc_u32 s37, s37, 0
	global_load_dwordx2 v[32:33], v3, s[36:37]
	s_add_u32 s33, s0, 0x21000
	s_addc_u32 s34, s1, 0
	s_mov_b32 s36, s33
	s_mov_b32 s37, s34
	global_load_dwordx2 v[16:17], v3, s[36:37]
	s_add_u32 s36, s36, 0x5800
	s_addc_u32 s37, s37, 0
	global_load_dwordx2 v[34:35], v3, s[36:37]
	s_add_u32 s33, s0, 0x2c000
	s_addc_u32 s34, s1, 0
	s_mov_b32 s36, s33
	s_mov_b32 s37, s34
	global_load_dwordx2 v[18:19], v3, s[36:37]
	s_add_u32 s36, s36, 0x5800
	s_addc_u32 s37, s37, 0
	global_load_dwordx2 v[36:37], v3, s[36:37]
	s_add_u32 s33, s0, 0x37000
	s_addc_u32 s34, s1, 0
	s_mov_b32 s36, s33
	s_mov_b32 s37, s34
	global_load_dwordx2 v[20:21], v3, s[36:37]
	s_add_u32 s36, s36, 0x5800
	s_addc_u32 s37, s37, 0
	global_load_dwordx2 v[38:39], v3, s[36:37]
	s_add_u32 s33, s0, 0x42000
	s_addc_u32 s34, s1, 0
	s_mov_b32 s36, s33
	s_mov_b32 s37, s34
	global_load_dwordx2 v[22:23], v3, s[36:37]
	s_add_u32 s36, s36, 0x5800
	s_addc_u32 s37, s37, 0
	global_load_dwordx2 v[40:41], v3, s[36:37]
	s_add_u32 s33, s0, 0x4d000
	s_addc_u32 s34, s1, 0
	s_mov_b32 s36, s33
	s_mov_b32 s37, s34
	global_load_dwordx2 v[24:25], v3, s[36:37]
	s_add_u32 s36, s36, 0x5800
	s_addc_u32 s37, s37, 0
	global_load_dwordx2 v[42:43], v3, s[36:37]
	s_add_u32 s33, s0, 0x58000
	s_addc_u32 s34, s1, 0
	s_mov_b32 s36, s33
	s_mov_b32 s37, s34
	global_load_dwordx2 v[26:27], v3, s[36:37]
	s_add_u32 s36, s36, 0x5800
	s_addc_u32 s37, s37, 0
	global_load_dwordx2 v[44:45], v3, s[36:37]
	global_load_dwordx2 v[46:47], v3, s[2:3]
	s_add_u32 s36, s2, 0x5800
	s_addc_u32 s37, s3, 0
	global_load_dwordx2 v[48:49], v3, s[36:37]
	global_load_dword v172, v1, s[8:9]
	global_load_dword v173, v2, s[8:9]
	s_add_u32 s8, s8, 0x5800
	s_addc_u32 s9, s9, 0
	global_load_dword v174, v1, s[8:9]
	global_load_dword v175, v2, s[8:9]
	s_add_u32 s8, s8, 0x5800
	s_addc_u32 s9, s9, 0
	global_load_dword v156, v1, s[8:9]
	global_load_dword v157, v2, s[8:9]
	s_add_u32 s8, s8, 0x5800
	s_addc_u32 s9, s9, 0
	global_load_dword v158, v1, s[8:9]
	global_load_dword v159, v2, s[8:9]
	s_add_u32 s8, s8, 0x5800
	s_addc_u32 s9, s9, 0
	global_load_dword v160, v1, s[8:9]
	global_load_dword v161, v2, s[8:9]
	s_add_u32 s8, s8, 0x5800
	s_addc_u32 s9, s9, 0
	global_load_dword v162, v1, s[8:9]
	global_load_dword v163, v2, s[8:9]
	s_add_u32 s8, s8, 0x5800
	s_addc_u32 s9, s9, 0
	global_load_dword v164, v1, s[8:9]
	global_load_dword v165, v2, s[8:9]
	s_add_u32 s8, s8, 0x5800
	s_addc_u32 s9, s9, 0
	global_load_dword v166, v1, s[8:9]
	global_load_dword v167, v2, s[8:9]
	s_add_u32 s8, s8, 0x5800
	s_addc_u32 s9, s9, 0
	global_load_dword v168, v1, s[8:9]
	global_load_dword v169, v2, s[8:9]
	s_add_u32 s8, s8, 0x5800
	s_addc_u32 s9, s9, 0
	global_load_dword v170, v1, s[8:9]
	global_load_dword v171, v2, s[8:9]
	s_add_u32 s8, s8, 0x5800
	s_addc_u32 s9, s9, 0
	s_waitcnt vmcnt(16)
	v_and_b32_e32 v172, s30, v172
	v_and_b32_e32 v173, s30, v173
	v_lshlrev_b32_e32 v50, 16, v172
	v_and_b32_e32 v51, 0xffff0000, v172
	v_lshlrev_b32_e32 v52, 16, v173
	v_and_b32_e32 v53, 0xffff0000, v173
	v_lshlrev_b32_e32 v74, 16, v174
	v_and_b32_e32 v75, 0xffff0000, v174
	v_lshlrev_b32_e32 v76, 16, v175
	v_and_b32_e32 v77, 0xffff0000, v175
	global_load_dword v172, v1, s[8:9]
	global_load_dword v173, v2, s[8:9]
	s_add_u32 s8, s8, 0x5800
	s_addc_u32 s9, s9, 0
	global_load_dword v174, v1, s[8:9]
	global_load_dword v175, v2, s[8:9]
	s_add_u32 s8, s8, 0x5800
	s_addc_u32 s9, s9, 0
	global_load_dword v176, v1, s[8:9]
	global_load_dword v177, v2, s[8:9]
	s_add_u32 s8, s8, 0x5800
	s_addc_u32 s9, s9, 0
	global_load_dword v178, v1, s[8:9]
	global_load_dword v179, v2, s[8:9]
	s_add_u32 s8, s8, 0x5800
	s_addc_u32 s9, s9, 0
	global_load_dword v180, v1, s[8:9]
	global_load_dword v181, v2, s[8:9]
	s_add_u32 s8, s8, 0x5800
	s_addc_u32 s9, s9, 0
	global_load_dword v182, v1, s[8:9]
	global_load_dword v183, v2, s[8:9]
	s_add_u32 s8, s8, 0x5800
	s_addc_u32 s9, s9, 0
	global_load_dword v184, v1, s[8:9]
	global_load_dword v185, v2, s[8:9]
	s_add_u32 s8, s8, 0x5800
	s_addc_u32 s9, s9, 0
	global_load_dword v186, v1, s[8:9]
	global_load_dword v187, v2, s[8:9]
	s_add_u32 s8, s8, 0x5800
	s_addc_u32 s9, s9, 0
	s_mov_b32 s32, 0
.Lffn_p9_loop_ctx8:
	s_cmp_eq_u32 s32, 7
	s_cselect_b32 s42, s31, -1
	s_cmp_lg_u32 s32, 0
	s_cbranch_scc1 .Lffn_p9_wn10
	s_waitcnt vmcnt(16)
	s_branch .Lffn_p9_we9
.Lffn_p9_wn10:
	s_waitcnt vmcnt(24)
.Lffn_p9_we9:
	v_lshlrev_b32_e32 v98, 16, v156
	v_and_b32_e32 v99, 0xffff0000, v156
	v_lshlrev_b32_e32 v100, 16, v157
	v_and_b32_e32 v101, 0xffff0000, v157
	v_pk_fma_f32 v[146:147], v[16:17], v[50:51], v[46:47]
	v_pk_fma_f32 v[148:149], v[34:35], v[52:53], v[48:49]
	v_pk_fma_f32 v[146:147], v[18:19], v[74:75], v[146:147]
	v_pk_fma_f32 v[148:149], v[36:37], v[76:77], v[148:149]
	v_pk_fma_f32 v[146:147], v[20:21], v[98:99], v[146:147]
	v_pk_fma_f32 v[148:149], v[38:39], v[100:101], v[148:149]
	v_pk_mul_f32 v[150:151], v[146:147], v[4:5]
	v_exp_f32_e32 v150, v150
	v_exp_f32_e32 v151, v151
	s_nop 0
	v_pk_add_f32 v[150:151], v[150:151], v[6:7]
	v_rcp_f32_e32 v150, v150
	v_rcp_f32_e32 v151, v151
	s_nop 0
	v_pk_mul_f32 v[150:151], v[150:151], v[146:147]
	v_pk_mul_f32 v[150:151], v[150:151], v[148:149]
	v_cvt_pk_bf16_f32 v204, v150, v151
	global_store_dword v1, v204, s[20:21]
	s_add_u32 s20, s20, 0x2c00
	s_addc_u32 s21, s21, 0
	v_lshlrev_b32_e32 v122, 16, v158
	v_and_b32_e32 v123, 0xffff0000, v158
	v_lshlrev_b32_e32 v124, 16, v159
	v_and_b32_e32 v125, 0xffff0000, v159
	v_pk_fma_f32 v[146:147], v[16:17], v[74:75], v[46:47]
	v_pk_fma_f32 v[148:149], v[34:35], v[76:77], v[48:49]
	v_pk_fma_f32 v[146:147], v[18:19], v[98:99], v[146:147]
	v_pk_fma_f32 v[148:149], v[36:37], v[100:101], v[148:149]
	v_pk_fma_f32 v[146:147], v[20:21], v[122:123], v[146:147]
	v_pk_fma_f32 v[148:149], v[38:39], v[124:125], v[148:149]
	v_pk_mul_f32 v[150:151], v[146:147], v[4:5]
	v_exp_f32_e32 v150, v150
	v_exp_f32_e32 v151, v151
	s_nop 0
	v_pk_add_f32 v[150:151], v[150:151], v[6:7]
	v_rcp_f32_e32 v150, v150
	v_rcp_f32_e32 v151, v151
	s_nop 0
	v_pk_mul_f32 v[150:151], v[150:151], v[146:147]
	v_pk_mul_f32 v[150:151], v[150:151], v[148:149]
	v_cvt_pk_bf16_f32 v205, v150, v151
	global_store_dword v1, v205, s[20:21]
	s_add_u32 s20, s20, 0x2c00
	s_addc_u32 s21, s21, 0
	v_lshlrev_b32_e32 v50, 16, v160
	v_and_b32_e32 v51, 0xffff0000, v160
	v_lshlrev_b32_e32 v52, 16, v161
	v_and_b32_e32 v53, 0xffff0000, v161
	v_pk_fma_f32 v[146:147], v[16:17], v[98:99], v[46:47]
	v_pk_fma_f32 v[148:149], v[34:35], v[100:101], v[48:49]
	v_pk_fma_f32 v[146:147], v[18:19], v[122:123], v[146:147]
	v_pk_fma_f32 v[148:149], v[36:37], v[124:125], v[148:149]
	v_pk_fma_f32 v[146:147], v[20:21], v[50:51], v[146:147]
	v_pk_fma_f32 v[148:149], v[38:39], v[52:53], v[148:149]
	v_pk_mul_f32 v[150:151], v[146:147], v[4:5]
	v_exp_f32_e32 v150, v150
	v_exp_f32_e32 v151, v151
	s_nop 0
	v_pk_add_f32 v[150:151], v[150:151], v[6:7]
	v_rcp_f32_e32 v150, v150
	v_rcp_f32_e32 v151, v151
	s_nop 0
	v_pk_mul_f32 v[150:151], v[150:151], v[146:147]
	v_pk_mul_f32 v[150:151], v[150:151], v[148:149]
	v_cvt_pk_bf16_f32 v206, v150, v151
	global_store_dword v1, v206, s[20:21]
	s_add_u32 s20, s20, 0x2c00
	s_addc_u32 s21, s21, 0
	v_lshlrev_b32_e32 v74, 16, v162
	v_and_b32_e32 v75, 0xffff0000, v162
	v_lshlrev_b32_e32 v76, 16, v163
	v_and_b32_e32 v77, 0xffff0000, v163
	v_pk_fma_f32 v[146:147], v[16:17], v[122:123], v[46:47]
	v_pk_fma_f32 v[148:149], v[34:35], v[124:125], v[48:49]
	v_pk_fma_f32 v[146:147], v[18:19], v[50:51], v[146:147]
	v_pk_fma_f32 v[148:149], v[36:37], v[52:53], v[148:149]
	v_pk_fma_f32 v[146:147], v[20:21], v[74:75], v[146:147]
	v_pk_fma_f32 v[148:149], v[38:39], v[76:77], v[148:149]
	v_pk_mul_f32 v[150:151], v[146:147], v[4:5]
	v_exp_f32_e32 v150, v150
	v_exp_f32_e32 v151, v151
	s_nop 0
	v_pk_add_f32 v[150:151], v[150:151], v[6:7]
	v_rcp_f32_e32 v150, v150
	v_rcp_f32_e32 v151, v151
	s_nop 0
	v_pk_mul_f32 v[150:151], v[150:151], v[146:147]
	v_pk_mul_f32 v[150:151], v[150:151], v[148:149]
	v_cvt_pk_bf16_f32 v207, v150, v151
	global_store_dword v1, v207, s[20:21]
	s_add_u32 s20, s20, 0x2c00
	s_addc_u32 s21, s21, 0
	v_lshlrev_b32_e32 v98, 16, v164
	v_and_b32_e32 v99, 0xffff0000, v164
	v_lshlrev_b32_e32 v100, 16, v165
	v_and_b32_e32 v101, 0xffff0000, v165
	v_pk_fma_f32 v[146:147], v[16:17], v[50:51], v[46:47]
	v_pk_fma_f32 v[148:149], v[34:35], v[52:53], v[48:49]
	v_pk_fma_f32 v[146:147], v[18:19], v[74:75], v[146:147]
	v_pk_fma_f32 v[148:149], v[36:37], v[76:77], v[148:149]
	v_pk_fma_f32 v[146:147], v[20:21], v[98:99], v[146:147]
	v_pk_fma_f32 v[148:149], v[38:39], v[100:101], v[148:149]
	v_pk_mul_f32 v[150:151], v[146:147], v[4:5]
	v_exp_f32_e32 v150, v150
	v_exp_f32_e32 v151, v151
	s_nop 0
	v_pk_add_f32 v[150:151], v[150:151], v[6:7]
	v_rcp_f32_e32 v150, v150
	v_rcp_f32_e32 v151, v151
	s_nop 0
	v_pk_mul_f32 v[150:151], v[150:151], v[146:147]
	v_pk_mul_f32 v[150:151], v[150:151], v[148:149]
	v_cvt_pk_bf16_f32 v204, v150, v151
	global_store_dword v1, v204, s[20:21]
	s_add_u32 s20, s20, 0x2c00
	s_addc_u32 s21, s21, 0
	v_lshlrev_b32_e32 v122, 16, v166
	v_and_b32_e32 v123, 0xffff0000, v166
	v_lshlrev_b32_e32 v124, 16, v167
	v_and_b32_e32 v125, 0xffff0000, v167
	v_pk_fma_f32 v[146:147], v[16:17], v[74:75], v[46:47]
	v_pk_fma_f32 v[148:149], v[34:35], v[76:77], v[48:49]
	v_pk_fma_f32 v[146:147], v[18:19], v[98:99], v[146:147]
	v_pk_fma_f32 v[148:149], v[36:37], v[100:101], v[148:149]
	v_pk_fma_f32 v[146:147], v[20:21], v[122:123], v[146:147]
	v_pk_fma_f32 v[148:149], v[38:39], v[124:125], v[148:149]
	v_pk_mul_f32 v[150:151], v[146:147], v[4:5]
	v_exp_f32_e32 v150, v150
	v_exp_f32_e32 v151, v151
	s_nop 0
	v_pk_add_f32 v[150:151], v[150:151], v[6:7]
	v_rcp_f32_e32 v150, v150
	v_rcp_f32_e32 v151, v151
	s_nop 0
	v_pk_mul_f32 v[150:151], v[150:151], v[146:147]
	v_pk_mul_f32 v[150:151], v[150:151], v[148:149]
	v_cvt_pk_bf16_f32 v205, v150, v151
	global_store_dword v1, v205, s[20:21]
	s_add_u32 s20, s20, 0x2c00
	s_addc_u32 s21, s21, 0
	v_lshlrev_b32_e32 v50, 16, v168
	v_and_b32_e32 v51, 0xffff0000, v168
	v_lshlrev_b32_e32 v52, 16, v169
	v_and_b32_e32 v53, 0xffff0000, v169
	v_pk_fma_f32 v[146:147], v[16:17], v[98:99], v[46:47]
	v_pk_fma_f32 v[148:149], v[34:35], v[100:101], v[48:49]
	v_pk_fma_f32 v[146:147], v[18:19], v[122:123], v[146:147]
	v_pk_fma_f32 v[148:149], v[36:37], v[124:125], v[148:149]
	v_pk_fma_f32 v[146:147], v[20:21], v[50:51], v[146:147]
	v_pk_fma_f32 v[148:149], v[38:39], v[52:53], v[148:149]
	v_pk_mul_f32 v[150:151], v[146:147], v[4:5]
	v_exp_f32_e32 v150, v150
	v_exp_f32_e32 v151, v151
	s_nop 0
	v_pk_add_f32 v[150:151], v[150:151], v[6:7]
	v_rcp_f32_e32 v150, v150
	v_rcp_f32_e32 v151, v151
	s_nop 0
	v_pk_mul_f32 v[150:151], v[150:151], v[146:147]
	v_pk_mul_f32 v[150:151], v[150:151], v[148:149]
	v_cvt_pk_bf16_f32 v206, v150, v151
	global_store_dword v1, v206, s[20:21]
	s_add_u32 s20, s20, 0x2c00
	s_addc_u32 s21, s21, 0
	v_lshlrev_b32_e32 v74, 16, v170
	v_and_b32_e32 v75, 0xffff0000, v170
	v_lshlrev_b32_e32 v76, 16, v171
	v_and_b32_e32 v77, 0xffff0000, v171
	v_pk_fma_f32 v[146:147], v[16:17], v[122:123], v[46:47]
	v_pk_fma_f32 v[148:149], v[34:35], v[124:125], v[48:49]
	v_pk_fma_f32 v[146:147], v[18:19], v[50:51], v[146:147]
	v_pk_fma_f32 v[148:149], v[36:37], v[52:53], v[148:149]
	v_pk_fma_f32 v[146:147], v[20:21], v[74:75], v[146:147]
	v_pk_fma_f32 v[148:149], v[38:39], v[76:77], v[148:149]
	v_pk_mul_f32 v[150:151], v[146:147], v[4:5]
	v_exp_f32_e32 v150, v150
	v_exp_f32_e32 v151, v151
	s_nop 0
	v_pk_add_f32 v[150:151], v[150:151], v[6:7]
	v_rcp_f32_e32 v150, v150
	v_rcp_f32_e32 v151, v151
	s_nop 0
	v_pk_mul_f32 v[150:151], v[150:151], v[146:147]
	v_pk_mul_f32 v[150:151], v[150:151], v[148:149]
	v_cvt_pk_bf16_f32 v207, v150, v151
	global_store_dword v1, v207, s[20:21]
	s_add_u32 s20, s20, 0x2c00
	s_addc_u32 s21, s21, 0
	s_cmp_eq_u32 s32, 7
	s_cbranch_scc1 .Lffn_p9_skipld11
	global_load_dword v156, v1, s[8:9]
	global_load_dword v157, v2, s[8:9]
	s_add_u32 s8, s8, 0x5800
	s_addc_u32 s9, s9, 0
	global_load_dword v158, v1, s[8:9]
	global_load_dword v159, v2, s[8:9]
	s_add_u32 s8, s8, 0x5800
	s_addc_u32 s9, s9, 0
	global_load_dword v160, v1, s[8:9]
	global_load_dword v161, v2, s[8:9]
	s_add_u32 s8, s8, 0x5800
	s_addc_u32 s9, s9, 0
	global_load_dword v162, v1, s[8:9]
	global_load_dword v163, v2, s[8:9]
	s_add_u32 s8, s8, 0x5800
	s_addc_u32 s9, s9, 0
	global_load_dword v164, v1, s[8:9]
	global_load_dword v165, v2, s[8:9]
	s_add_u32 s8, s8, 0x5800
	s_addc_u32 s9, s9, 0
	global_load_dword v166, v1, s[8:9]
	global_load_dword v167, v2, s[8:9]
	s_add_u32 s8, s8, 0x5800
	s_addc_u32 s9, s9, 0
	global_load_dword v168, v1, s[8:9]
	global_load_dword v169, v2, s[8:9]
	s_add_u32 s8, s8, 0x5800
	s_addc_u32 s9, s9, 0
	global_load_dword v170, v1, s[8:9]
	global_load_dword v171, v2, s[8:9]
	s_add_u32 s8, s8, 0x5800
	s_addc_u32 s9, s9, 0

.Lffn_p9_we12:
	v_lshlrev_b32_e32 v98, 16, v172
	v_and_b32_e32 v99, 0xffff0000, v172
	v_lshlrev_b32_e32 v100, 16, v173
	v_and_b32_e32 v101, 0xffff0000, v173
	v_pk_fma_f32 v[146:147], v[16:17], v[50:51], v[46:47]
	v_pk_fma_f32 v[148:149], v[34:35], v[52:53], v[48:49]
	v_pk_fma_f32 v[146:147], v[18:19], v[74:75], v[146:147]
	v_pk_fma_f32 v[148:149], v[36:37], v[76:77], v[148:149]
	v_pk_fma_f32 v[146:147], v[20:21], v[98:99], v[146:147]
	v_pk_fma_f32 v[148:149], v[38:39], v[100:101], v[148:149]
	v_pk_mul_f32 v[150:151], v[146:147], v[4:5]
	v_exp_f32_e32 v150, v150
	v_exp_f32_e32 v151, v151
	s_nop 0
	v_pk_add_f32 v[150:151], v[150:151], v[6:7]
	v_rcp_f32_e32 v150, v150
	v_rcp_f32_e32 v151, v151
	s_nop 0
	v_pk_mul_f32 v[150:151], v[150:151], v[146:147]
	v_pk_mul_f32 v[150:151], v[150:151], v[148:149]
	v_cvt_pk_bf16_f32 v204, v150, v151
	global_store_dword v1, v204, s[20:21]
	s_add_u32 s20, s20, 0x2c00
	s_addc_u32 s21, s21, 0
	v_lshlrev_b32_e32 v122, 16, v174
	v_and_b32_e32 v123, 0xffff0000, v174
	v_lshlrev_b32_e32 v124, 16, v175
	v_and_b32_e32 v125, 0xffff0000, v175
	v_pk_fma_f32 v[146:147], v[16:17], v[74:75], v[46:47]
	v_pk_fma_f32 v[148:149], v[34:35], v[76:77], v[48:49]
	v_pk_fma_f32 v[146:147], v[18:19], v[98:99], v[146:147]
	v_pk_fma_f32 v[148:149], v[36:37], v[100:101], v[148:149]
	v_pk_fma_f32 v[146:147], v[20:21], v[122:123], v[146:147]
	v_pk_fma_f32 v[148:149], v[38:39], v[124:125], v[148:149]
	v_pk_mul_f32 v[150:151], v[146:147], v[4:5]
	v_exp_f32_e32 v150, v150
	v_exp_f32_e32 v151, v151
	s_nop 0
	v_pk_add_f32 v[150:151], v[150:151], v[6:7]
	v_rcp_f32_e32 v150, v150
	v_rcp_f32_e32 v151, v151
	s_nop 0
	v_pk_mul_f32 v[150:151], v[150:151], v[146:147]
	v_pk_mul_f32 v[150:151], v[150:151], v[148:149]
	v_cvt_pk_bf16_f32 v205, v150, v151
	global_store_dword v1, v205, s[20:21]
	s_add_u32 s20, s20, 0x2c00
	s_addc_u32 s21, s21, 0
	v_lshlrev_b32_e32 v50, 16, v176
	v_and_b32_e32 v51, 0xffff0000, v176
	v_lshlrev_b32_e32 v52, 16, v177
	v_and_b32_e32 v53, 0xffff0000, v177
	v_pk_fma_f32 v[146:147], v[16:17], v[98:99], v[46:47]
	v_pk_fma_f32 v[148:149], v[34:35], v[100:101], v[48:49]
	v_pk_fma_f32 v[146:147], v[18:19], v[122:123], v[146:147]
	v_pk_fma_f32 v[148:149], v[36:37], v[124:125], v[148:149]
	v_pk_fma_f32 v[146:147], v[20:21], v[50:51], v[146:147]
	v_pk_fma_f32 v[148:149], v[38:39], v[52:53], v[148:149]
	v_pk_mul_f32 v[150:151], v[146:147], v[4:5]
	v_exp_f32_e32 v150, v150
	v_exp_f32_e32 v151, v151
	s_nop 0
	v_pk_add_f32 v[150:151], v[150:151], v[6:7]
	v_rcp_f32_e32 v150, v150
	v_rcp_f32_e32 v151, v151
	s_nop 0
	v_pk_mul_f32 v[150:151], v[150:151], v[146:147]
	v_pk_mul_f32 v[150:151], v[150:151], v[148:149]
	v_cvt_pk_bf16_f32 v206, v150, v151
	global_store_dword v1, v206, s[20:21]
	s_add_u32 s20, s20, 0x2c00
	s_addc_u32 s21, s21, 0
	v_lshlrev_b32_e32 v74, 16, v178
	v_and_b32_e32 v75, 0xffff0000, v178
	v_lshlrev_b32_e32 v76, 16, v179
	v_and_b32_e32 v77, 0xffff0000, v179
	v_pk_fma_f32 v[146:147], v[16:17], v[122:123], v[46:47]
	v_pk_fma_f32 v[148:149], v[34:35], v[124:125], v[48:49]
	v_pk_fma_f32 v[146:147], v[18:19], v[50:51], v[146:147]
	v_pk_fma_f32 v[148:149], v[36:37], v[52:53], v[148:149]
	v_pk_fma_f32 v[146:147], v[20:21], v[74:75], v[146:147]
	v_pk_fma_f32 v[148:149], v[38:39], v[76:77], v[148:149]
	v_pk_mul_f32 v[150:151], v[146:147], v[4:5]
	v_exp_f32_e32 v150, v150
	v_exp_f32_e32 v151, v151
	s_nop 0
	v_pk_add_f32 v[150:151], v[150:151], v[6:7]
	v_rcp_f32_e32 v150, v150
	v_rcp_f32_e32 v151, v151
	s_nop 0
	v_pk_mul_f32 v[150:151], v[150:151], v[146:147]
	v_pk_mul_f32 v[150:151], v[150:151], v[148:149]
	v_cvt_pk_bf16_f32 v207, v150, v151
	global_store_dword v1, v207, s[20:21]
	s_add_u32 s20, s20, 0x2c00
	s_addc_u32 s21, s21, 0
	v_lshlrev_b32_e32 v98, 16, v180
	v_and_b32_e32 v99, 0xffff0000, v180
	v_lshlrev_b32_e32 v100, 16, v181
	v_and_b32_e32 v101, 0xffff0000, v181
	v_pk_fma_f32 v[146:147], v[16:17], v[50:51], v[46:47]
	v_pk_fma_f32 v[148:149], v[34:35], v[52:53], v[48:49]
	v_pk_fma_f32 v[146:147], v[18:19], v[74:75], v[146:147]
	v_pk_fma_f32 v[148:149], v[36:37], v[76:77], v[148:149]
	v_pk_fma_f32 v[146:147], v[20:21], v[98:99], v[146:147]
	v_pk_fma_f32 v[148:149], v[38:39], v[100:101], v[148:149]
	v_pk_mul_f32 v[150:151], v[146:147], v[4:5]
	v_exp_f32_e32 v150, v150
	v_exp_f32_e32 v151, v151
	s_nop 0
	v_pk_add_f32 v[150:151], v[150:151], v[6:7]
	v_rcp_f32_e32 v150, v150
	v_rcp_f32_e32 v151, v151
	s_nop 0
	v_pk_mul_f32 v[150:151], v[150:151], v[146:147]
	v_pk_mul_f32 v[150:151], v[150:151], v[148:149]
	v_cvt_pk_bf16_f32 v204, v150, v151
	global_store_dword v1, v204, s[20:21]
	s_add_u32 s20, s20, 0x2c00
	s_addc_u32 s21, s21, 0
	v_lshlrev_b32_e32 v122, 16, v182
	v_and_b32_e32 v123, 0xffff0000, v182
	v_lshlrev_b32_e32 v124, 16, v183
	v_and_b32_e32 v125, 0xffff0000, v183
	v_pk_fma_f32 v[146:147], v[16:17], v[74:75], v[46:47]
	v_pk_fma_f32 v[148:149], v[34:35], v[76:77], v[48:49]
	v_pk_fma_f32 v[146:147], v[18:19], v[98:99], v[146:147]
	v_pk_fma_f32 v[148:149], v[36:37], v[100:101], v[148:149]
	v_pk_fma_f32 v[146:147], v[20:21], v[122:123], v[146:147]
	v_pk_fma_f32 v[148:149], v[38:39], v[124:125], v[148:149]
	v_pk_mul_f32 v[150:151], v[146:147], v[4:5]
	v_exp_f32_e32 v150, v150
	v_exp_f32_e32 v151, v151
	s_nop 0
	v_pk_add_f32 v[150:151], v[150:151], v[6:7]
	v_rcp_f32_e32 v150, v150
	v_rcp_f32_e32 v151, v151
	s_nop 0
	v_pk_mul_f32 v[150:151], v[150:151], v[146:147]
	v_pk_mul_f32 v[150:151], v[150:151], v[148:149]
	v_cvt_pk_bf16_f32 v205, v150, v151
	global_store_dword v1, v205, s[20:21]
	s_add_u32 s20, s20, 0x2c00
	s_addc_u32 s21, s21, 0
	v_lshlrev_b32_e32 v50, 16, v184
	v_and_b32_e32 v51, 0xffff0000, v184
	v_lshlrev_b32_e32 v52, 16, v185
	v_and_b32_e32 v53, 0xffff0000, v185
	v_pk_fma_f32 v[146:147], v[16:17], v[98:99], v[46:47]
	v_pk_fma_f32 v[148:149], v[34:35], v[100:101], v[48:49]
	v_pk_fma_f32 v[146:147], v[18:19], v[122:123], v[146:147]
	v_pk_fma_f32 v[148:149], v[36:37], v[124:125], v[148:149]
	v_pk_fma_f32 v[146:147], v[20:21], v[50:51], v[146:147]
	v_pk_fma_f32 v[148:149], v[38:39], v[52:53], v[148:149]
	v_pk_mul_f32 v[150:151], v[146:147], v[4:5]
	v_exp_f32_e32 v150, v150
	v_exp_f32_e32 v151, v151
	s_nop 0
	v_pk_add_f32 v[150:151], v[150:151], v[6:7]
	v_rcp_f32_e32 v150, v150
	v_rcp_f32_e32 v151, v151
	s_nop 0
	v_pk_mul_f32 v[150:151], v[150:151], v[146:147]
	v_pk_mul_f32 v[150:151], v[150:151], v[148:149]
	v_cvt_pk_bf16_f32 v206, v150, v151
	global_store_dword v1, v206, s[20:21]
	s_add_u32 s20, s20, 0x2c00
	s_addc_u32 s21, s21, 0
	v_and_b32_e32 v186, s42, v186
	v_and_b32_e32 v187, s42, v187
	v_lshlrev_b32_e32 v74, 16, v186
	v_and_b32_e32 v75, 0xffff0000, v186
	v_lshlrev_b32_e32 v76, 16, v187
	v_and_b32_e32 v77, 0xffff0000, v187
	v_pk_fma_f32 v[146:147], v[16:17], v[122:123], v[46:47]
	v_pk_fma_f32 v[148:149], v[34:35], v[124:125], v[48:49]
	v_pk_fma_f32 v[146:147], v[18:19], v[50:51], v[146:147]
	v_pk_fma_f32 v[148:149], v[36:37], v[52:53], v[148:149]
	v_pk_fma_f32 v[146:147], v[20:21], v[74:75], v[146:147]
	v_pk_fma_f32 v[148:149], v[38:39], v[76:77], v[148:149]
	v_pk_mul_f32 v[150:151], v[146:147], v[4:5]
	v_exp_f32_e32 v150, v150
	v_exp_f32_e32 v151, v151
	s_nop 0
	v_pk_add_f32 v[150:151], v[150:151], v[6:7]
	v_rcp_f32_e32 v150, v150
	v_rcp_f32_e32 v151, v151
	s_nop 0
	v_pk_mul_f32 v[150:151], v[150:151], v[146:147]
	v_pk_mul_f32 v[150:151], v[150:151], v[148:149]
	v_cvt_pk_bf16_f32 v207, v150, v151
	global_store_dword v1, v207, s[20:21]
	s_add_u32 s20, s20, 0x2c00
	s_addc_u32 s21, s21, 0
	s_cmp_eq_u32 s32, 7
	s_cbranch_scc1 .Lffn_p9_skipld14
	global_load_dword v172, v1, s[8:9]
	global_load_dword v173, v2, s[8:9]
	s_add_u32 s8, s8, 0x5800
	s_addc_u32 s9, s9, 0
	global_load_dword v174, v1, s[8:9]
	global_load_dword v175, v2, s[8:9]
	s_add_u32 s8, s8, 0x5800
	s_addc_u32 s9, s9, 0
	global_load_dword v176, v1, s[8:9]
	global_load_dword v177, v2, s[8:9]
	s_add_u32 s8, s8, 0x5800
	s_addc_u32 s9, s9, 0
	global_load_dword v178, v1, s[8:9]
	global_load_dword v179, v2, s[8:9]
	s_add_u32 s8, s8, 0x5800
	s_addc_u32 s9, s9, 0
	global_load_dword v180, v1, s[8:9]
	global_load_dword v181, v2, s[8:9]
	s_add_u32 s8, s8, 0x5800
	s_addc_u32 s9, s9, 0
	global_load_dword v182, v1, s[8:9]
	global_load_dword v183, v2, s[8:9]
	s_add_u32 s8, s8, 0x5800
	s_addc_u32 s9, s9, 0
	global_load_dword v184, v1, s[8:9]
	global_load_dword v185, v2, s[8:9]
	s_add_u32 s8, s8, 0x5800
	s_addc_u32 s9, s9, 0
	global_load_dword v186, v1, s[8:9]
	global_load_dword v187, v2, s[8:9]
	s_add_u32 s8, s8, 0x5800
	s_addc_u32 s9, s9, 0
.Lffn_p9_skipld14:
	s_add_u32 s32, s32, 1
	s_cmp_lt_u32 s32, 8
	s_cbranch_scc1 .Lffn_p9_loop_ctx8
.Lffn_p9_itemend:
	s_waitcnt vmcnt(0)
	v_readfirstlane_b32 s6, v8
	s_branch .Lffn_p9_item
.Lffn_p9_done:
	s_waitcnt vmcnt(0)
	s_branch .LBB0_1326
